# M1 and M3 weight-fragment prologues: load groups software-pipelined one deep (next group's 8 loads issued before the previous group's wait)
# speedup vs baseline: 1.0271x; 1.0020x over previous
; #define LAS __attribute__((address_space(3)))
; __device__ __forceinline__ ArgP largs() { ArgP p = (ArgP)__builtin_amdgcn_kernarg_segment_ptr(); asm volatile("" : "+s"(p)); return p; }
; __device__ __forceinline__ unsigned xb_add(unsigned* p, unsigned v) { return __hip_atomic_fetch_add(p, v, __ATOMIC_RELAXED, __HIP_MEMORY_SCOPE_AGENT); }
; __device__ __forceinline__ unsigned xb_xcc_id() { return (unsigned)__builtin_amdgcn_s_getreg((3 << 11) | 20) & 0xFu; }
; __device__ __forceinline__ XcdBarrier xcd_barrier_post(unsigned* bar, volatile LAS unsigned* st) {
;     XcdBarrier b; b.bar = bar; b.x = xb_xcc_id(); b.st = st;
;     if (threadIdx.x == 0) (void)xb_add(&bar[XB_XCNT(b.x)], 1u);
;     return b;
; __global__ void __launch_bounds__(NTHR, 2) mega_fwd(Args A_unused) {
;     extern __shared__ __attribute__((aligned(16))) unsigned char lds_[];
;     cg::grid_group grid = cg::this_grid();
;     LAS unsigned char* lds = (LAS unsigned char*)lds_;
;     const int bid = blockIdx.x, G = gridDim.x;
;     volatile LAS unsigned* xst = (volatile LAS unsigned*)(lds + LDS_BYTES - 64);
;     if (threadIdx.x < 16) xst[threadIdx.x] = 0u;
;     __syncthreads();
;     XcdBarrier xbar; { ArgP A = largs(); xbar = xcd_barrier_post((unsigned*)(A->ws + WS_CTL), xst); }
_Z8mega_fwd4Args:
	s_mov_b64 s[68:69], s[0:1]
	s_load_dwordx2 s[92:93], s[0:1], 0x148
	s_load_dword s33, s[0:1], 0x150
	s_add_u32 s0, s68, 0x148
	s_addc_u32 s1, s69, 0
	v_and_b32_e32 v195, 0x3ff, v0
	v_writelane_b32 v251, s0, 0
	s_mov_b32 s70, s2
	v_cmp_gt_u32_e32 vcc, 16, v195
	v_writelane_b32 v251, s1, 1
	s_and_saveexec_b64 s[0:1], vcc
	v_lshl_add_u32 v1, v195, 2, 0
	v_add_u32_e32 v1, 0x23fc0, v1
	v_mov_b32_e32 v2, 0
	ds_write_b32 v1, v2
	s_or_b64 exec, exec, s[0:1]
	s_mov_b64 s[0:1], s[68:69]
	s_waitcnt lgkmcnt(0)
	s_barrier
	v_readfirstlane_b32 s2, v195
	s_cmpk_lt_u32 s2, 0x100
	s_cbranch_scc1 .Lprio_skip
	s_setprio 1
.Lprio_skip:
	s_load_dwordx2 s[0:1], s[0:1], 0x138
	s_getreg_b32 s2, hwreg(HW_REG_XCC_ID, 0, 4)
	v_cmp_eq_u32_e64 s[72:73], 0, v195
	s_waitcnt lgkmcnt(0)
	s_add_u32 s6, s0, 0x2ac00000
	s_addc_u32 s7, s1, 0
	s_and_b32 s50, s2, 15
	s_and_saveexec_b64 s[2:3], s[72:73]
	s_cbranch_execz .LBB0_5
	s_mov_b64 s[4:5], exec
	v_mbcnt_lo_u32_b32 v1, s4, 0
	v_mbcnt_hi_u32_b32 v1, s5, v1
	v_cmp_eq_u32_e32 vcc, 0, v1
	s_and_b64 s[8:9], exec, vcc
	s_mov_b64 exec, s[8:9]
	s_cbranch_execz .LBB0_5
	s_lshl_b32 s8, s50, 8
	s_bcnt1_i32_b64 s4, s[4:5]
	v_mov_b32_e32 v1, s8
	v_mov_b32_e32 v2, s4
	global_atomic_add v1, v2, s[6:7] offset:1024

; #define LAS __attribute__((address_space(3)))
; __device__ __forceinline__ bf16x8 pack8(const float (&t)[8]) { u32x4 w; w.x = pk2(t[0], t[1]); w.y = pk2(t[2], t[3]); w.z = pk2(t[4], t[5]); w.w = pk2(t[6], t[7]); return __builtin_bit_cast(bf16x8, w); }
; __device__ __forceinline__ void m1_phase(ArgP A, int layer, LAS unsigned char* lds, int tid, int lane, int wave, int bid, int G) {
;     ...
;     bf16x8 bw[4];
; #pragma unroll
;     for (int ct = 0; ct < 4; ++ct) { const int n = h * 64 + ct * 16 + c; float tb[8];
; #pragma unroll
;         for (int j = 0; j < 8; ++j) tb[j] = wl[(quad * 8 + j) * 512 + n];
;         bw[ct] = pack8(tb);
; #pragma unroll
;         for (int j = 0; j < 8; ++j) tb[j] = al[(quad * 8 + j) * 512 + n];
;         *(LAS bf16x8*)(fr + ct * 1024) = pack8(tb);
; #pragma unroll
;         for (int kk = 0; kk < 3; ++kk) {
; #pragma unroll
;             for (int j = 0; j < 8; ++j) tb[j] = gl[(kk * 32 + quad * 8 + j) * 512 + n];
;             *(LAS bf16x8*)(fr + (4 + kk * 4 + ct) * 1024) = pack8(tb); } }
.LBB0_292:
	s_cmp_le_i32 s74, s18
	s_cselect_b64 s[6:7], -1, 0
	s_and_b64 s[0:1], s[6:7], s[4:5]
	s_andn2_b64 vcc, exec, s[0:1]
	s_cbranch_vccnz .LBB0_550
	s_waitcnt vmcnt(0)
	v_mov_b32_e32 v18, v195
	s_mov_b64 s[8:9], s[68:69]
	s_load_dwordx16 s[40:55], s[8:9], 0x68
	v_readfirstlane_b32 s1, v18
	v_and_b32_e32 v138, 15, v18
	v_bfe_u32 v19, v18, 4, 2
	s_and_b32 s4, s1, 0xffffffc0
	s_ashr_i32 s14, s1, 6
	v_readlane_b32 s10, v254, 10
	v_or_b32_e32 v74, s4, v138
	v_lshlrev_b32_e32 v16, 12, v19
	s_lshl_b32 s82, s10, 14
	s_lshl_b32 s0, s14, 14
	v_add_u32_e32 v0, v74, v16
	s_add_i32 s0, s0, 0
	v_add_u32_e32 v6, 0x800, v0
	v_add_u32_e32 v8, 0xa00, v0
	v_add_u32_e32 v12, 0xe00, v0
	s_lshl_b64 s[2:3], s[82:83], 2
	v_ashrrev_i32_e32 v1, 31, v0
	v_add_u32_e32 v2, 0x400, v0
	v_add_u32_e32 v4, 0x600, v0
	v_ashrrev_i32_e32 v7, 31, v6
	v_ashrrev_i32_e32 v9, 31, v8
	v_add_u32_e32 v10, 0xc00, v0
	v_ashrrev_i32_e32 v13, 31, v12
	s_waitcnt lgkmcnt(0)
	s_add_u32 s12, s42, s2
	v_ashrrev_i32_e32 v3, 31, v2
	v_ashrrev_i32_e32 v5, 31, v4
	v_ashrrev_i32_e32 v11, 31, v10
	s_addc_u32 s13, s43, s3
	v_lshlrev_b64 v[14:15], 2, v[0:1]
	v_lshlrev_b64 v[6:7], 2, v[6:7]
	v_lshlrev_b64 v[8:9], 2, v[8:9]
	v_lshlrev_b64 v[12:13], 2, v[12:13]
	v_lshl_add_u64 v[0:1], s[12:13], 0, v[14:15]
	v_lshlrev_b64 v[2:3], 2, v[2:3]
	v_lshlrev_b64 v[4:5], 2, v[4:5]
	v_lshl_add_u64 v[24:25], s[12:13], 0, v[6:7]
	v_lshl_add_u64 v[26:27], s[12:13], 0, v[8:9]
	v_lshlrev_b64 v[10:11], 2, v[10:11]
	v_lshl_add_u64 v[28:29], s[12:13], 0, v[12:13]
	v_lshl_add_u64 v[20:21], s[12:13], 0, v[2:3]
	v_lshl_add_u64 v[22:23], s[12:13], 0, v[4:5]
	global_load_dword v30, v[0:1], off offset:2048
	global_load_dword v31, v[20:21], off
	s_nop 0
	global_load_dword v28, v[28:29], off
	s_nop 0
	global_load_dword v26, v[26:27], off
	s_nop 0
	global_load_dword v27, v[22:23], off
	global_load_dword v29, v[0:1], off
	v_lshl_add_u64 v[0:1], s[12:13], 0, v[10:11]
	global_load_dword v24, v[24:25], off
	s_nop 0
	global_load_dword v25, v[0:1], off
	s_add_u32 s16, s46, s2
	s_addc_u32 s17, s47, s3
	v_lshl_add_u64 v[20:21], s[16:17], 0, v[14:15]
	v_lshl_add_u64 v[4:5], s[16:17], 0, v[4:5]
	v_lshl_add_u64 v[6:7], s[16:17], 0, v[6:7]
	v_lshl_add_u64 v[22:23], s[16:17], 0, v[2:3]
	v_lshl_add_u64 v[8:9], s[16:17], 0, v[8:9]
	v_lshl_add_u64 v[12:13], s[16:17], 0, v[12:13]
	s_mul_i32 s2, s10, 0xc000
	s_mov_b32 s3, s83
	s_lshl_b64 s[2:3], s[2:3], 2
	v_readlane_b32 s11, v254, 11
	v_ashrrev_i32_e32 v75, 31, v74
	s_add_u32 s10, s50, s2
	s_addc_u32 s11, s51, s3
	v_lshl_add_u64 v[14:15], s[10:11], 0, v[14:15]
	v_or_b32_e32 v76, 32, v74
	v_ashrrev_i32_e32 v77, 31, v76
	global_load_dword v150, v[20:21], off offset:2048
	global_load_dword v36, v[22:23], off
	global_load_dword v37, v[12:13], off
	global_load_dword v38, v[8:9], off
	global_load_dword v39, v[4:5], off
	s_nop 0
	global_load_dword v20, v[20:21], off
	v_lshl_add_u64 v[4:5], s[16:17], 0, v[10:11]
	global_load_dword v40, v[6:7], off
	global_load_dword v41, v[4:5], off
	s_waitcnt vmcnt(8)
	v_cvt_pk_bf16_f32 v0, v29, v30
	v_cvt_pk_bf16_f32 v1, v31, v27
	v_cvt_pk_bf16_f32 v2, v24, v26
	v_cvt_pk_bf16_f32 v3, v25, v28
	v_or_b32_e32 v22, 0x600, v16
	v_or_b32_e32 v23, 0x800, v16
	v_or_b32_e32 v24, 0xa00, v16
	v_or_b32_e32 v21, 0x400, v16
	v_or_b32_e32 v25, 0xc00, v16
	v_or_b32_e32 v26, 0xe00, v16
	v_add_u32_e32 v6, v22, v74
	v_add_u32_e32 v8, v23, v74
	v_add_u32_e32 v10, v24, v74
	v_add_u32_e32 v4, v21, v74
	v_add_u32_e32 v12, v25, v74
	v_add_u32_e32 v28, v26, v74
	v_ashrrev_i32_e32 v7, 31, v6
	v_ashrrev_i32_e32 v9, 31, v8
	v_ashrrev_i32_e32 v11, 31, v10
	v_lshl_add_u64 v[30:31], v[16:17], 0, v[74:75]
	v_ashrrev_i32_e32 v5, 31, v4
	v_ashrrev_i32_e32 v13, 31, v12
	v_ashrrev_i32_e32 v29, 31, v28
	v_lshl_add_u64 v[30:31], v[30:31], 2, s[10:11]
	v_lshl_add_u64 v[34:35], v[6:7], 2, s[10:11]
	v_lshl_add_u64 v[8:9], v[8:9], 2, s[10:11]
	v_lshl_add_u64 v[10:11], v[10:11], 2, s[10:11]
	v_lshl_add_u64 v[32:33], v[4:5], 2, s[10:11]
	v_lshl_add_u64 v[28:29], v[28:29], 2, s[10:11]
	global_load_dword v151, v[30:31], off offset:2048
	global_load_dword v44, v[32:33], off
	global_load_dword v45, v[28:29], off
	global_load_dword v46, v[10:11], off
	s_nop 0
	global_load_dword v35, v[34:35], off
	s_nop 0
	global_load_dword v47, v[14:15], off
	v_lshl_add_u64 v[10:11], v[12:13], 2, s[10:11]
	global_load_dword v48, v[8:9], off
	global_load_dword v49, v[10:11], off
	s_waitcnt vmcnt(10)
	v_cvt_pk_bf16_f32 v4, v20, v150
	v_cvt_pk_bf16_f32 v5, v36, v39
	s_waitcnt vmcnt(9)
	v_cvt_pk_bf16_f32 v6, v40, v38
	s_waitcnt vmcnt(8)
	v_cvt_pk_bf16_f32 v7, v41, v37
	v_and_b32_e32 v8, 63, v18
	v_or_b32_e32 v27, 0x4000, v16
	v_or_b32_e32 v28, 0x4200, v16
	v_or_b32_e32 v31, 0x4800, v16
	v_or_b32_e32 v34, 0x4e00, v16
	v_lshlrev_b32_e32 v9, 4, v8
	v_or_b32_e32 v29, 0x4400, v16
	v_or_b32_e32 v30, 0x4600, v16
	v_or_b32_e32 v32, 0x4a00, v16
	v_or_b32_e32 v33, 0x4c00, v16
	v_add_u32_e32 v8, v27, v74
	v_add_u32_e32 v10, v28, v74
	v_add_u32_e32 v36, v31, v74
	v_add_u32_e32 v42, v34, v74
	v_add_u32_e32 v12, v29, v74
	v_add_u32_e32 v14, v30, v74
	v_add_u32_e32 v38, v32, v74
	v_add_u32_e32 v40, v33, v74
	v_add_u32_e32 v139, s0, v9
	v_ashrrev_i32_e32 v9, 31, v8
	v_ashrrev_i32_e32 v11, 31, v10
	v_ashrrev_i32_e32 v37, 31, v36
	v_ashrrev_i32_e32 v43, 31, v42
	v_ashrrev_i32_e32 v13, 31, v12
	v_ashrrev_i32_e32 v15, 31, v14
	v_ashrrev_i32_e32 v39, 31, v38
	v_ashrrev_i32_e32 v41, 31, v40
	v_lshl_add_u64 v[8:9], v[8:9], 2, s[10:11]
	v_lshl_add_u64 v[10:11], v[10:11], 2, s[10:11]
	v_lshl_add_u64 v[36:37], v[36:37], 2, s[10:11]
	v_lshl_add_u64 v[42:43], v[42:43], 2, s[10:11]
	v_lshl_add_u64 v[12:13], v[12:13], 2, s[10:11]
	v_lshl_add_u64 v[14:15], v[14:15], 2, s[10:11]
	v_lshl_add_u64 v[38:39], v[38:39], 2, s[10:11]
	global_load_dword v20, v[10:11], off
	global_load_dword v52, v[12:13], off
	s_nop 0
	global_load_dword v43, v[42:43], off
	s_nop 0
	global_load_dword v53, v[38:39], off
	global_load_dword v54, v[14:15], off
	global_load_dword v55, v[8:9], off
	v_lshl_add_u64 v[8:9], v[40:41], 2, s[10:11]
	global_load_dword v56, v[36:37], off
	global_load_dword v57, v[8:9], off
	ds_write_b128 v139, v[4:7]
	s_waitcnt vmcnt(10)
; #define LAS __attribute__((address_space(3)))
; __device__ __forceinline__ bf16x8 pack8(const float (&t)[8]) { u32x4 w; w.x = pk2(t[0], t[1]); w.y = pk2(t[2], t[3]); w.z = pk2(t[4], t[5]); w.w = pk2(t[6], t[7]); return __builtin_bit_cast(bf16x8, w); }
; __device__ __forceinline__ void m1_phase(ArgP A, int layer, LAS unsigned char* lds, int tid, int lane, int wave, int bid, int G) {
;     ...
; #pragma unroll
;     for (int ct = 0; ct < 4; ++ct) { const int n = h * 64 + ct * 16 + c; float tb[8];
; #pragma unroll
;         for (int j = 0; j < 8; ++j) tb[j] = wl[(quad * 8 + j) * 512 + n];
;         bw[ct] = pack8(tb);
; #pragma unroll
;         for (int j = 0; j < 8; ++j) tb[j] = al[(quad * 8 + j) * 512 + n];
;         *(LAS bf16x8*)(fr + ct * 1024) = pack8(tb);
; #pragma unroll
;         for (int kk = 0; kk < 3; ++kk) {
; #pragma unroll
;             for (int j = 0; j < 8; ++j) tb[j] = gl[(kk * 32 + quad * 8 + j) * 512 + n];
;             *(LAS bf16x8*)(fr + (4 + kk * 4 + ct) * 1024) = pack8(tb); } }
	v_cvt_pk_bf16_f32 v4, v47, v151
	v_cvt_pk_bf16_f32 v5, v44, v35
	s_waitcnt vmcnt(9)
	v_cvt_pk_bf16_f32 v6, v48, v46
	s_waitcnt vmcnt(8)
	v_cvt_pk_bf16_f32 v7, v49, v45
	v_or_b32_e32 v35, 0x8000, v16
	v_or_b32_e32 v36, 0x8200, v16
	v_or_b32_e32 v37, 0x8400, v16
	v_or_b32_e32 v38, 0x8600, v16
	v_or_b32_e32 v39, 0x8800, v16
	v_or_b32_e32 v40, 0x8a00, v16
	v_or_b32_e32 v41, 0x8c00, v16
	v_or_b32_e32 v42, 0x8e00, v16
	v_add_u32_e32 v8, v35, v74
	v_add_u32_e32 v10, v36, v74
	v_add_u32_e32 v12, v37, v74
	v_add_u32_e32 v14, v38, v74
	v_add_u32_e32 v44, v39, v74
	v_add_u32_e32 v46, v40, v74
	v_add_u32_e32 v48, v41, v74
	v_add_u32_e32 v50, v42, v74
	v_ashrrev_i32_e32 v9, 31, v8
	v_ashrrev_i32_e32 v11, 31, v10
	v_ashrrev_i32_e32 v13, 31, v12
	v_ashrrev_i32_e32 v15, 31, v14
	v_ashrrev_i32_e32 v45, 31, v44
	v_ashrrev_i32_e32 v47, 31, v46
	v_ashrrev_i32_e32 v49, 31, v48
	v_ashrrev_i32_e32 v51, 31, v50
	v_lshl_add_u64 v[8:9], v[8:9], 2, s[10:11]
	v_lshl_add_u64 v[10:11], v[10:11], 2, s[10:11]
	v_lshl_add_u64 v[12:13], v[12:13], 2, s[10:11]
	v_lshl_add_u64 v[14:15], v[14:15], 2, s[10:11]
	v_lshl_add_u64 v[44:45], v[44:45], 2, s[10:11]
	v_lshl_add_u64 v[46:47], v[46:47], 2, s[10:11]
	v_lshl_add_u64 v[50:51], v[50:51], 2, s[10:11]
	global_load_dword v152, v[10:11], off
	global_load_dword v153, v[12:13], off
	global_load_dword v64, v[50:51], off
	global_load_dword v65, v[46:47], off
	global_load_dword v66, v[14:15], off
	global_load_dword v67, v[8:9], off
	v_lshl_add_u64 v[8:9], v[48:49], 2, s[10:11]
	global_load_dword v68, v[44:45], off
	s_nop 0
	global_load_dword v9, v[8:9], off
	ds_write_b128 v139, v[4:7] offset:4096
	s_waitcnt vmcnt(10)
	v_cvt_pk_bf16_f32 v4, v55, v20
	v_cvt_pk_bf16_f32 v5, v52, v54
	s_waitcnt vmcnt(9)
	v_cvt_pk_bf16_f32 v6, v56, v53
	s_waitcnt vmcnt(8)
	v_cvt_pk_bf16_f32 v7, v57, v43
	v_or_b32_e32 v8, 16, v74
	v_add_u32_e32 v10, v8, v16
	v_add_u32_e32 v12, 0x400, v10
	v_add_u32_e32 v14, 0x600, v10
	v_add_u32_e32 v44, 0x800, v10
	v_ashrrev_i32_e32 v11, 31, v10
	v_add_u32_e32 v46, 0xa00, v10
	v_add_u32_e32 v48, 0xc00, v10
	v_add_u32_e32 v50, 0xe00, v10
	v_ashrrev_i32_e32 v13, 31, v12
	v_ashrrev_i32_e32 v15, 31, v14
	v_ashrrev_i32_e32 v45, 31, v44
	v_ashrrev_i32_e32 v47, 31, v46
	v_ashrrev_i32_e32 v49, 31, v48
	v_ashrrev_i32_e32 v51, 31, v50
	v_lshlrev_b64 v[10:11], 2, v[10:11]
	v_lshlrev_b64 v[12:13], 2, v[12:13]
	v_lshlrev_b64 v[14:15], 2, v[14:15]
	v_lshlrev_b64 v[44:45], 2, v[44:45]
	v_lshl_add_u64 v[52:53], s[12:13], 0, v[10:11]
	v_lshlrev_b64 v[46:47], 2, v[46:47]
	v_lshlrev_b64 v[48:49], 2, v[48:49]
	v_lshlrev_b64 v[50:51], 2, v[50:51]
	v_lshl_add_u64 v[54:55], s[12:13], 0, v[12:13]
	v_lshl_add_u64 v[56:57], s[12:13], 0, v[14:15]
	v_lshl_add_u64 v[58:59], s[12:13], 0, v[44:45]
	v_lshl_add_u64 v[60:61], s[12:13], 0, v[46:47]
	v_lshl_add_u64 v[62:63], s[12:13], 0, v[50:51]
	global_load_dword v154, v[52:53], off offset:2048
	global_load_dword v20, v[54:55], off
	global_load_dword v43, v[62:63], off
	s_nop 0
	global_load_dword v54, v[60:61], off
	global_load_dword v55, v[56:57], off
	s_nop 0
	global_load_dword v56, v[52:53], off
	v_lshl_add_u64 v[52:53], s[12:13], 0, v[48:49]
	global_load_dword v57, v[58:59], off
	s_nop 0
	global_load_dword v58, v[52:53], off
	ds_write_b128 v139, v[4:7] offset:8192
	s_waitcnt vmcnt(10)
	v_cvt_pk_bf16_f32 v4, v67, v152
	v_cvt_pk_bf16_f32 v5, v153, v66
	s_waitcnt vmcnt(9)
	v_cvt_pk_bf16_f32 v6, v68, v65
	s_waitcnt vmcnt(8)
	v_cvt_pk_bf16_f32 v7, v9, v64
	v_lshl_add_u64 v[52:53], s[16:17], 0, v[10:11]
	v_lshl_add_u64 v[12:13], s[16:17], 0, v[12:13]
	v_lshl_add_u64 v[44:45], s[16:17], 0, v[44:45]
	v_lshl_add_u64 v[14:15], s[16:17], 0, v[14:15]
	v_lshl_add_u64 v[46:47], s[16:17], 0, v[46:47]
	v_lshl_add_u64 v[50:51], s[16:17], 0, v[50:51]
	global_load_dword v155, v[52:53], off offset:2048
	global_load_dword v156, v[12:13], off
	global_load_dword v157, v[50:51], off
	global_load_dword v59, v[46:47], off
	global_load_dword v60, v[14:15], off
	global_load_dword v61, v[52:53], off
	v_lshl_add_u64 v[12:13], s[16:17], 0, v[48:49]
	global_load_dword v62, v[44:45], off
	global_load_dword v63, v[12:13], off
	ds_write_b128 v139, v[4:7] offset:12288
	v_readlane_b32 s0, v252, 13
	v_readlane_b32 s1, v252, 14
	s_andn2_b64 vcc, exec, s[0:1]
	s_waitcnt vmcnt(10)
	v_cvt_pk_bf16_f32 v4, v56, v154
	v_cvt_pk_bf16_f32 v5, v20, v55
	s_waitcnt vmcnt(9)
	v_cvt_pk_bf16_f32 v6, v57, v54
	s_waitcnt vmcnt(8)
	v_cvt_pk_bf16_f32 v7, v58, v43
	v_add_u32_e32 v14, v22, v8
	v_add_u32_e32 v44, v23, v8
	v_ashrrev_i32_e32 v9, 31, v8
	v_add_u32_e32 v12, v21, v8
	v_add_u32_e32 v46, v24, v8
	v_add_u32_e32 v48, v25, v8
	v_add_u32_e32 v50, v26, v8
	v_ashrrev_i32_e32 v15, 31, v14
	v_ashrrev_i32_e32 v45, 31, v44
	v_lshl_add_u64 v[52:53], v[16:17], 0, v[8:9]
	v_ashrrev_i32_e32 v13, 31, v12
	v_ashrrev_i32_e32 v47, 31, v46
	v_ashrrev_i32_e32 v49, 31, v48
	v_ashrrev_i32_e32 v51, 31, v50
	v_lshl_add_u64 v[52:53], v[52:53], 2, s[10:11]
	v_lshl_add_u64 v[14:15], v[14:15], 2, s[10:11]
	v_lshl_add_u64 v[44:45], v[44:45], 2, s[10:11]
	v_lshl_add_u64 v[54:55], s[10:11], 0, v[10:11]
	v_lshl_add_u64 v[56:57], v[12:13], 2, s[10:11]
	v_lshl_add_u64 v[46:47], v[46:47], 2, s[10:11]
	v_lshl_add_u64 v[50:51], v[50:51], 2, s[10:11]
	global_load_dword v9, v[52:53], off offset:2048
	global_load_dword v20, v[56:57], off
	global_load_dword v43, v[50:51], off
	global_load_dword v58, v[46:47], off
	global_load_dword v150, v[14:15], off
	global_load_dword v151, v[54:55], off
	v_lshl_add_u64 v[14:15], v[48:49], 2, s[10:11]
	global_load_dword v152, v[44:45], off
	global_load_dword v153, v[14:15], off
	s_waitcnt vmcnt(10)
	v_cvt_pk_bf16_f32 v10, v61, v155
	v_cvt_pk_bf16_f32 v11, v156, v60
	s_waitcnt vmcnt(9)
; #define LAS __attribute__((address_space(3)))
; __device__ __forceinline__ bf16x8 pack8(const float (&t)[8]) { u32x4 w; w.x = pk2(t[0], t[1]); w.y = pk2(t[2], t[3]); w.z = pk2(t[4], t[5]); w.w = pk2(t[6], t[7]); return __builtin_bit_cast(bf16x8, w); }
; #define LDS_WAIT() asm volatile("s_waitcnt lgkmcnt(0)" ::: "memory")
; __device__ __forceinline__ void m1_phase(ArgP A, int layer, LAS unsigned char* lds, int tid, int lane, int wave, int bid, int G) {
;     ...
;     bf16x8 bw[4];
; #pragma unroll
;     for (int ct = 0; ct < 4; ++ct) { const int n = h * 64 + ct * 16 + c; float tb[8];
; #pragma unroll
;         for (int j = 0; j < 8; ++j) tb[j] = wl[(quad * 8 + j) * 512 + n];
;         bw[ct] = pack8(tb);
; #pragma unroll
;         for (int j = 0; j < 8; ++j) tb[j] = al[(quad * 8 + j) * 512 + n];
;         *(LAS bf16x8*)(fr + ct * 1024) = pack8(tb);
; #pragma unroll
;         for (int kk = 0; kk < 3; ++kk) {
; #pragma unroll
;             for (int j = 0; j < 8; ++j) tb[j] = gl[(kk * 32 + quad * 8 + j) * 512 + n];
;             *(LAS bf16x8*)(fr + (4 + kk * 4 + ct) * 1024) = pack8(tb); } }
;     LDS_WAIT();
	v_cvt_pk_bf16_f32 v12, v62, v59
	s_waitcnt vmcnt(8)
	v_cvt_pk_bf16_f32 v13, v63, v157
	v_add_u32_e32 v14, v27, v8
	v_add_u32_e32 v44, v28, v8
	v_add_u32_e32 v50, v31, v8
	v_add_u32_e32 v46, v29, v8
	v_add_u32_e32 v48, v30, v8
	v_add_u32_e32 v52, v32, v8
	v_add_u32_e32 v54, v33, v8
	v_add_u32_e32 v56, v34, v8
	v_ashrrev_i32_e32 v15, 31, v14
	v_ashrrev_i32_e32 v45, 31, v44
	v_ashrrev_i32_e32 v51, 31, v50
	v_ashrrev_i32_e32 v47, 31, v46
	v_ashrrev_i32_e32 v49, 31, v48
	v_ashrrev_i32_e32 v53, 31, v52
	v_ashrrev_i32_e32 v55, 31, v54
	v_ashrrev_i32_e32 v57, 31, v56
	v_lshl_add_u64 v[14:15], v[14:15], 2, s[10:11]
	v_lshl_add_u64 v[44:45], v[44:45], 2, s[10:11]
	v_lshl_add_u64 v[50:51], v[50:51], 2, s[10:11]
	v_lshl_add_u64 v[46:47], v[46:47], 2, s[10:11]
	v_lshl_add_u64 v[48:49], v[48:49], 2, s[10:11]
	v_lshl_add_u64 v[52:53], v[52:53], 2, s[10:11]
	v_lshl_add_u64 v[56:57], v[56:57], 2, s[10:11]
	global_load_dword v154, v[44:45], off
	global_load_dword v155, v[46:47], off
	global_load_dword v156, v[56:57], off
	global_load_dword v59, v[52:53], off
	global_load_dword v60, v[48:49], off
	global_load_dword v61, v[14:15], off
	v_lshl_add_u64 v[14:15], v[54:55], 2, s[10:11]
	global_load_dword v62, v[50:51], off
	global_load_dword v63, v[14:15], off
	ds_write_b128 v139, v[10:13] offset:1024
	s_waitcnt vmcnt(10)
	v_cvt_pk_bf16_f32 v10, v151, v9
	v_cvt_pk_bf16_f32 v11, v20, v150
	s_waitcnt vmcnt(9)
	v_cvt_pk_bf16_f32 v12, v152, v58
	s_waitcnt vmcnt(8)
	v_cvt_pk_bf16_f32 v13, v153, v43
	v_add_u32_e32 v44, v36, v8
	v_add_u32_e32 v50, v39, v8
	v_add_u32_e32 v14, v35, v8
	v_add_u32_e32 v46, v37, v8
	v_add_u32_e32 v48, v38, v8
	v_add_u32_e32 v52, v40, v8
	v_add_u32_e32 v54, v41, v8
	v_add_u32_e32 v8, v42, v8
	v_ashrrev_i32_e32 v45, 31, v44
	v_ashrrev_i32_e32 v51, 31, v50
	v_ashrrev_i32_e32 v15, 31, v14
	v_ashrrev_i32_e32 v47, 31, v46
	v_ashrrev_i32_e32 v49, 31, v48
	v_ashrrev_i32_e32 v53, 31, v52
	v_ashrrev_i32_e32 v55, 31, v54
	v_ashrrev_i32_e32 v9, 31, v8
	v_lshl_add_u64 v[44:45], v[44:45], 2, s[10:11]
	v_lshl_add_u64 v[50:51], v[50:51], 2, s[10:11]
	v_lshl_add_u64 v[14:15], v[14:15], 2, s[10:11]
	v_lshl_add_u64 v[46:47], v[46:47], 2, s[10:11]
	v_lshl_add_u64 v[48:49], v[48:49], 2, s[10:11]
	v_lshl_add_u64 v[52:53], v[52:53], 2, s[10:11]
	v_lshl_add_u64 v[56:57], v[8:9], 2, s[10:11]
	ds_write_b128 v139, v[10:13] offset:5120
	s_waitcnt vmcnt(2)
	v_cvt_pk_bf16_f32 v8, v61, v154
	v_cvt_pk_bf16_f32 v9, v155, v60
	s_waitcnt vmcnt(1)
	v_cvt_pk_bf16_f32 v10, v62, v59
	s_waitcnt vmcnt(0)
	v_cvt_pk_bf16_f32 v11, v63, v156
	global_load_dword v20, v[44:45], off
	global_load_dword v43, v[46:47], off
	global_load_dword v66, v[56:57], off
	global_load_dword v67, v[52:53], off
	global_load_dword v68, v[48:49], off
	global_load_dword v69, v[14:15], off
	v_lshl_add_u64 v[12:13], v[54:55], 2, s[10:11]
	global_load_dword v70, v[50:51], off
	global_load_dword v71, v[12:13], off
	v_add_u32_e32 v12, v76, v16
	v_add_u32_e32 v14, 0x400, v12
	v_add_u32_e32 v44, 0x600, v12
	v_add_u32_e32 v46, 0x800, v12
	v_ashrrev_i32_e32 v13, 31, v12
	v_add_u32_e32 v48, 0xa00, v12
	v_add_u32_e32 v50, 0xc00, v12
	v_add_u32_e32 v52, 0xe00, v12
	v_ashrrev_i32_e32 v15, 31, v14
	v_ashrrev_i32_e32 v45, 31, v44
	v_ashrrev_i32_e32 v47, 31, v46
	v_ashrrev_i32_e32 v49, 31, v48
	v_ashrrev_i32_e32 v51, 31, v50
	v_ashrrev_i32_e32 v53, 31, v52
	v_lshlrev_b64 v[12:13], 2, v[12:13]
	v_lshlrev_b64 v[14:15], 2, v[14:15]
	v_lshlrev_b64 v[44:45], 2, v[44:45]
	v_lshlrev_b64 v[46:47], 2, v[46:47]
	v_lshl_add_u64 v[54:55], s[12:13], 0, v[12:13]
	v_lshlrev_b64 v[48:49], 2, v[48:49]
	v_lshlrev_b64 v[50:51], 2, v[50:51]
	v_lshlrev_b64 v[52:53], 2, v[52:53]
	v_lshl_add_u64 v[56:57], s[12:13], 0, v[14:15]
	v_lshl_add_u64 v[58:59], s[12:13], 0, v[44:45]
	v_lshl_add_u64 v[60:61], s[12:13], 0, v[46:47]
	v_lshl_add_u64 v[62:63], s[12:13], 0, v[48:49]
	v_lshl_add_u64 v[64:65], s[12:13], 0, v[52:53]
	global_load_dword v157, v[54:55], off offset:2048
	global_load_dword v150, v[56:57], off
	s_nop 0
	global_load_dword v56, v[64:65], off
	global_load_dword v57, v[62:63], off
	s_nop 0
	global_load_dword v58, v[58:59], off
	s_nop 0
	global_load_dword v59, v[54:55], off
	v_lshl_add_u64 v[54:55], s[12:13], 0, v[50:51]
	global_load_dword v60, v[60:61], off
	s_nop 0
	global_load_dword v61, v[54:55], off
	ds_write_b128 v139, v[8:11] offset:9216
	s_waitcnt vmcnt(10)
	v_cvt_pk_bf16_f32 v8, v69, v20
	v_cvt_pk_bf16_f32 v9, v43, v68
	s_waitcnt vmcnt(9)
	v_cvt_pk_bf16_f32 v10, v70, v67
	s_waitcnt vmcnt(8)
	v_cvt_pk_bf16_f32 v11, v71, v66
	v_lshl_add_u64 v[54:55], s[16:17], 0, v[12:13]
	v_lshl_add_u64 v[14:15], s[16:17], 0, v[14:15]
	v_lshl_add_u64 v[46:47], s[16:17], 0, v[46:47]
	v_lshl_add_u64 v[44:45], s[16:17], 0, v[44:45]
	v_lshl_add_u64 v[48:49], s[16:17], 0, v[48:49]
	v_lshl_add_u64 v[52:53], s[16:17], 0, v[52:53]
	global_load_dword v20, v[54:55], off offset:2048
	global_load_dword v43, v[14:15], off
	global_load_dword v151, v[52:53], off
	global_load_dword v152, v[48:49], off
	global_load_dword v62, v[44:45], off
	global_load_dword v63, v[54:55], off
	v_lshl_add_u64 v[14:15], s[16:17], 0, v[50:51]
	global_load_dword v64, v[46:47], off
	global_load_dword v65, v[14:15], off
	ds_write_b128 v139, v[8:11] offset:13312
	s_waitcnt vmcnt(10)
	v_cvt_pk_bf16_f32 v8, v59, v157
	v_cvt_pk_bf16_f32 v9, v150, v58
	s_waitcnt vmcnt(9)
	v_cvt_pk_bf16_f32 v10, v60, v57
	s_waitcnt vmcnt(8)
; #define LAS __attribute__((address_space(3)))
; __device__ __forceinline__ bf16x8 pack8(const float (&t)[8]) { u32x4 w; w.x = pk2(t[0], t[1]); w.y = pk2(t[2], t[3]); w.z = pk2(t[4], t[5]); w.w = pk2(t[6], t[7]); return __builtin_bit_cast(bf16x8, w); }
; #define LDS_WAIT() asm volatile("s_waitcnt lgkmcnt(0)" ::: "memory")
; __device__ __forceinline__ void m1_phase(ArgP A, int layer, LAS unsigned char* lds, int tid, int lane, int wave, int bid, int G) {
;     ...
;     bf16x8 bw[4];
; #pragma unroll
;     for (int ct = 0; ct < 4; ++ct) { const int n = h * 64 + ct * 16 + c; float tb[8];
; #pragma unroll
;         for (int j = 0; j < 8; ++j) tb[j] = wl[(quad * 8 + j) * 512 + n];
;         bw[ct] = pack8(tb);
; #pragma unroll
;         for (int j = 0; j < 8; ++j) tb[j] = al[(quad * 8 + j) * 512 + n];
;         *(LAS bf16x8*)(fr + ct * 1024) = pack8(tb);
; #pragma unroll
;         for (int kk = 0; kk < 3; ++kk) {
; #pragma unroll
;             for (int j = 0; j < 8; ++j) tb[j] = gl[(kk * 32 + quad * 8 + j) * 512 + n];
;             *(LAS bf16x8*)(fr + (4 + kk * 4 + ct) * 1024) = pack8(tb); } }
;     LDS_WAIT();
	v_cvt_pk_bf16_f32 v11, v61, v56
	v_add_u32_e32 v44, v22, v76
	v_add_u32_e32 v46, v23, v76
	v_add_u32_e32 v14, v21, v76
	v_add_u32_e32 v48, v24, v76
	v_add_u32_e32 v50, v25, v76
	v_add_u32_e32 v52, v26, v76
	v_ashrrev_i32_e32 v45, 31, v44
	v_ashrrev_i32_e32 v47, 31, v46
	v_lshl_add_u64 v[54:55], v[16:17], 0, v[76:77]
	v_ashrrev_i32_e32 v15, 31, v14
	v_ashrrev_i32_e32 v49, 31, v48
	v_ashrrev_i32_e32 v51, 31, v50
	v_ashrrev_i32_e32 v53, 31, v52
	v_lshl_add_u64 v[54:55], v[54:55], 2, s[10:11]
	v_lshl_add_u64 v[44:45], v[44:45], 2, s[10:11]
	v_lshl_add_u64 v[46:47], v[46:47], 2, s[10:11]
	v_lshl_add_u64 v[56:57], s[10:11], 0, v[12:13]
	v_lshl_add_u64 v[58:59], v[14:15], 2, s[10:11]
	v_lshl_add_u64 v[48:49], v[48:49], 2, s[10:11]
	v_lshl_add_u64 v[52:53], v[52:53], 2, s[10:11]
	global_load_dword v153, v[54:55], off offset:2048
	global_load_dword v154, v[58:59], off
	global_load_dword v60, v[52:53], off
	global_load_dword v61, v[48:49], off
	global_load_dword v155, v[44:45], off
	global_load_dword v156, v[56:57], off
	v_lshl_add_u64 v[44:45], v[50:51], 2, s[10:11]
	global_load_dword v157, v[46:47], off
	global_load_dword v150, v[44:45], off
	s_waitcnt vmcnt(10)
	v_cvt_pk_bf16_f32 v12, v63, v20
	v_cvt_pk_bf16_f32 v13, v43, v62
	s_waitcnt vmcnt(9)
	v_cvt_pk_bf16_f32 v14, v64, v152
	s_waitcnt vmcnt(8)
	v_cvt_pk_bf16_f32 v15, v65, v151
	v_add_u32_e32 v44, v27, v76
	v_add_u32_e32 v46, v28, v76
	v_add_u32_e32 v52, v31, v76
	v_add_u32_e32 v48, v29, v76
	v_add_u32_e32 v50, v30, v76
	v_add_u32_e32 v54, v32, v76
	v_add_u32_e32 v56, v33, v76
	v_add_u32_e32 v58, v34, v76
	v_ashrrev_i32_e32 v45, 31, v44
	v_ashrrev_i32_e32 v47, 31, v46
	v_ashrrev_i32_e32 v53, 31, v52
	v_ashrrev_i32_e32 v49, 31, v48
	v_ashrrev_i32_e32 v51, 31, v50
	v_ashrrev_i32_e32 v55, 31, v54
	v_ashrrev_i32_e32 v57, 31, v56
	v_ashrrev_i32_e32 v59, 31, v58
	v_lshl_add_u64 v[44:45], v[44:45], 2, s[10:11]
	v_lshl_add_u64 v[46:47], v[46:47], 2, s[10:11]
	v_lshl_add_u64 v[52:53], v[52:53], 2, s[10:11]
	v_lshl_add_u64 v[48:49], v[48:49], 2, s[10:11]
	v_lshl_add_u64 v[50:51], v[50:51], 2, s[10:11]
	v_lshl_add_u64 v[54:55], v[54:55], 2, s[10:11]
	v_lshl_add_u64 v[58:59], v[58:59], 2, s[10:11]
	global_load_dword v20, v[46:47], off
	global_load_dword v43, v[48:49], off
	global_load_dword v151, v[58:59], off
	global_load_dword v152, v[54:55], off
	global_load_dword v62, v[50:51], off
	global_load_dword v63, v[44:45], off
	v_lshl_add_u64 v[44:45], v[56:57], 2, s[10:11]
	global_load_dword v64, v[52:53], off
	global_load_dword v65, v[44:45], off
	ds_write_b128 v139, v[12:15] offset:2048
	s_waitcnt vmcnt(10)
	v_cvt_pk_bf16_f32 v12, v156, v153
	v_cvt_pk_bf16_f32 v13, v154, v155
	s_waitcnt vmcnt(9)
	v_cvt_pk_bf16_f32 v14, v157, v61
	s_waitcnt vmcnt(8)
	v_cvt_pk_bf16_f32 v15, v150, v60
	v_add_u32_e32 v44, v35, v76
	v_add_u32_e32 v46, v36, v76
	v_add_u32_e32 v52, v39, v76
	v_add_u32_e32 v48, v37, v76
	v_add_u32_e32 v50, v38, v76
	v_add_u32_e32 v54, v40, v76
	v_add_u32_e32 v56, v41, v76
	v_add_u32_e32 v58, v42, v76
	v_ashrrev_i32_e32 v45, 31, v44
	v_ashrrev_i32_e32 v47, 31, v46
	v_ashrrev_i32_e32 v53, 31, v52
	v_ashrrev_i32_e32 v49, 31, v48
	v_ashrrev_i32_e32 v51, 31, v50
	v_ashrrev_i32_e32 v55, 31, v54
	v_ashrrev_i32_e32 v57, 31, v56
	v_ashrrev_i32_e32 v59, 31, v58
	v_lshl_add_u64 v[44:45], v[44:45], 2, s[10:11]
	v_lshl_add_u64 v[46:47], v[46:47], 2, s[10:11]
	v_lshl_add_u64 v[52:53], v[52:53], 2, s[10:11]
	v_lshl_add_u64 v[48:49], v[48:49], 2, s[10:11]
	v_lshl_add_u64 v[50:51], v[50:51], 2, s[10:11]
	v_lshl_add_u64 v[54:55], v[54:55], 2, s[10:11]
	v_lshl_add_u64 v[58:59], v[58:59], 2, s[10:11]
	global_load_dword v153, v[46:47], off
	global_load_dword v70, v[48:49], off
	global_load_dword v71, v[58:59], off
	global_load_dword v72, v[54:55], off
	global_load_dword v73, v[50:51], off
	global_load_dword v78, v[44:45], off
	v_lshl_add_u64 v[44:45], v[56:57], 2, s[10:11]
	global_load_dword v79, v[52:53], off
	global_load_dword v80, v[44:45], off
	ds_write_b128 v139, v[12:15] offset:6144
	s_waitcnt vmcnt(10)
	v_cvt_pk_bf16_f32 v12, v63, v20
	v_cvt_pk_bf16_f32 v13, v43, v62
	s_waitcnt vmcnt(9)
	v_cvt_pk_bf16_f32 v14, v64, v152
	s_waitcnt vmcnt(8)
	v_cvt_pk_bf16_f32 v15, v65, v151
	v_or_b32_e32 v20, 48, v74
	v_add_u32_e32 v44, v20, v16
	v_add_u32_e32 v46, 0x400, v44
	v_add_u32_e32 v48, 0x600, v44
	v_add_u32_e32 v50, 0x800, v44
	v_add_u32_e32 v52, 0xa00, v44
	v_ashrrev_i32_e32 v45, 31, v44
	v_add_u32_e32 v54, 0xc00, v44
	v_add_u32_e32 v56, 0xe00, v44
	v_ashrrev_i32_e32 v47, 31, v46
	v_ashrrev_i32_e32 v49, 31, v48
	v_ashrrev_i32_e32 v51, 31, v50
	v_ashrrev_i32_e32 v53, 31, v52
	v_ashrrev_i32_e32 v55, 31, v54
	v_ashrrev_i32_e32 v57, 31, v56
	v_lshlrev_b64 v[44:45], 2, v[44:45]
	v_lshlrev_b64 v[46:47], 2, v[46:47]
	v_lshlrev_b64 v[48:49], 2, v[48:49]
	v_lshlrev_b64 v[50:51], 2, v[50:51]
	v_lshlrev_b64 v[52:53], 2, v[52:53]
	v_lshl_add_u64 v[58:59], s[12:13], 0, v[44:45]
	v_lshlrev_b64 v[54:55], 2, v[54:55]
	v_lshlrev_b64 v[56:57], 2, v[56:57]
	v_lshl_add_u64 v[60:61], s[12:13], 0, v[46:47]
	v_lshl_add_u64 v[62:63], s[12:13], 0, v[48:49]
	v_lshl_add_u64 v[64:65], s[12:13], 0, v[50:51]
	v_lshl_add_u64 v[66:67], s[12:13], 0, v[52:53]
	v_lshl_add_u64 v[68:69], s[12:13], 0, v[56:57]
	global_load_dword v43, v[58:59], off offset:2048
	s_nop 0
	global_load_dword v60, v[60:61], off
	s_nop 0
	global_load_dword v61, v[68:69], off
	s_nop 0
	global_load_dword v66, v[66:67], off
	s_nop 0
	global_load_dword v62, v[62:63], off
	s_nop 0
	global_load_dword v63, v[58:59], off
	v_lshl_add_u64 v[58:59], s[12:13], 0, v[54:55]
	global_load_dword v64, v[64:65], off
	s_nop 0
	global_load_dword v65, v[58:59], off
	ds_write_b128 v139, v[12:15] offset:10240
	s_waitcnt vmcnt(10)
; #define LAS __attribute__((address_space(3)))
; __device__ __forceinline__ bf16x8 pack8(const float (&t)[8]) { u32x4 w; w.x = pk2(t[0], t[1]); w.y = pk2(t[2], t[3]); w.z = pk2(t[4], t[5]); w.w = pk2(t[6], t[7]); return __builtin_bit_cast(bf16x8, w); }
; #define LDS_WAIT() asm volatile("s_waitcnt lgkmcnt(0)" ::: "memory")
; __device__ __forceinline__ void m1_phase(ArgP A, int layer, LAS unsigned char* lds, int tid, int lane, int wave, int bid, int G) {
;     ...
;     bf16x8 bw[4];
; #pragma unroll
;     for (int ct = 0; ct < 4; ++ct) { const int n = h * 64 + ct * 16 + c; float tb[8];
; #pragma unroll
;         for (int j = 0; j < 8; ++j) tb[j] = wl[(quad * 8 + j) * 512 + n];
;         bw[ct] = pack8(tb);
; #pragma unroll
;         for (int j = 0; j < 8; ++j) tb[j] = al[(quad * 8 + j) * 512 + n];
;         *(LAS bf16x8*)(fr + ct * 1024) = pack8(tb);
; #pragma unroll
;         for (int kk = 0; kk < 3; ++kk) {
; #pragma unroll
;             for (int j = 0; j < 8; ++j) tb[j] = gl[(kk * 32 + quad * 8 + j) * 512 + n];
;             *(LAS bf16x8*)(fr + (4 + kk * 4 + ct) * 1024) = pack8(tb); } }
;     LDS_WAIT();
	v_cvt_pk_bf16_f32 v12, v78, v153
	v_cvt_pk_bf16_f32 v13, v70, v73
	s_waitcnt vmcnt(9)
	v_cvt_pk_bf16_f32 v14, v79, v72
	s_waitcnt vmcnt(8)
	v_cvt_pk_bf16_f32 v15, v80, v71
	v_lshl_add_u64 v[58:59], s[16:17], 0, v[44:45]
	v_lshl_add_u64 v[46:47], s[16:17], 0, v[46:47]
	v_lshl_add_u64 v[50:51], s[16:17], 0, v[50:51]
	v_lshl_add_u64 v[48:49], s[16:17], 0, v[48:49]
	v_lshl_add_u64 v[52:53], s[16:17], 0, v[52:53]
	v_lshl_add_u64 v[56:57], s[16:17], 0, v[56:57]
	global_load_dword v154, v[58:59], off offset:2048
	global_load_dword v155, v[46:47], off
	global_load_dword v156, v[56:57], off
	global_load_dword v157, v[52:53], off
	global_load_dword v150, v[48:49], off
	global_load_dword v151, v[58:59], off
	v_lshl_add_u64 v[46:47], s[16:17], 0, v[54:55]
	global_load_dword v152, v[50:51], off
	global_load_dword v153, v[46:47], off
	ds_write_b128 v139, v[12:15] offset:14336
	s_waitcnt vmcnt(10)
	v_cvt_pk_bf16_f32 v12, v63, v43
	v_cvt_pk_bf16_f32 v13, v60, v62
	s_waitcnt vmcnt(9)
	v_cvt_pk_bf16_f32 v14, v64, v66
	s_waitcnt vmcnt(8)
	v_cvt_pk_bf16_f32 v15, v65, v61
	v_add_u32_e32 v46, v21, v20
	v_add_u32_e32 v22, v22, v20
	v_add_u32_e32 v48, v23, v20
	v_add_u32_e32 v52, v26, v20
	v_ashrrev_i32_e32 v21, 31, v20
	v_add_u32_e32 v24, v24, v20
	v_add_u32_e32 v50, v25, v20
	v_ashrrev_i32_e32 v23, 31, v22
	v_ashrrev_i32_e32 v49, 31, v48
	v_ashrrev_i32_e32 v53, 31, v52
	v_lshl_add_u64 v[54:55], v[16:17], 0, v[20:21]
	v_ashrrev_i32_e32 v47, 31, v46
	v_ashrrev_i32_e32 v25, 31, v24
	v_ashrrev_i32_e32 v51, 31, v50
	v_lshl_add_u64 v[44:45], s[10:11], 0, v[44:45]
	v_lshl_add_u64 v[54:55], v[54:55], 2, s[10:11]
	v_lshl_add_u64 v[56:57], v[22:23], 2, s[10:11]
	v_lshl_add_u64 v[48:49], v[48:49], 2, s[10:11]
	v_lshl_add_u64 v[52:53], v[52:53], 2, s[10:11]
	v_lshl_add_u64 v[46:47], v[46:47], 2, s[10:11]
	v_lshl_add_u64 v[58:59], v[24:25], 2, s[10:11]
	global_load_dword v16, v[54:55], off offset:2048
	global_load_dword v21, v[46:47], off
	global_load_dword v43, v[52:53], off
	s_nop 0
	global_load_dword v52, v[58:59], off
	global_load_dword v53, v[56:57], off
	global_load_dword v54, v[44:45], off
	v_lshl_add_u64 v[44:45], v[50:51], 2, s[10:11]
	global_load_dword v55, v[48:49], off
	global_load_dword v56, v[44:45], off
	s_waitcnt vmcnt(10)
	v_cvt_pk_bf16_f32 v22, v151, v154
	v_cvt_pk_bf16_f32 v23, v155, v150
	s_waitcnt vmcnt(9)
	v_cvt_pk_bf16_f32 v24, v152, v157
	s_waitcnt vmcnt(8)
	v_cvt_pk_bf16_f32 v25, v153, v156
	v_add_u32_e32 v26, v27, v20
	v_add_u32_e32 v28, v28, v20
	v_add_u32_e32 v44, v29, v20
	v_add_u32_e32 v46, v31, v20
	v_add_u32_e32 v50, v34, v20
	v_add_u32_e32 v30, v30, v20
	v_add_u32_e32 v32, v32, v20
	v_add_u32_e32 v48, v33, v20
	v_ashrrev_i32_e32 v27, 31, v26
	v_ashrrev_i32_e32 v29, 31, v28
	v_ashrrev_i32_e32 v45, 31, v44
	v_ashrrev_i32_e32 v47, 31, v46
	v_ashrrev_i32_e32 v51, 31, v50
	v_ashrrev_i32_e32 v31, 31, v30
	v_ashrrev_i32_e32 v33, 31, v32
	v_ashrrev_i32_e32 v49, 31, v48
	v_lshl_add_u64 v[26:27], v[26:27], 2, s[10:11]
	v_lshl_add_u64 v[28:29], v[28:29], 2, s[10:11]
	v_lshl_add_u64 v[44:45], v[44:45], 2, s[10:11]
	v_lshl_add_u64 v[46:47], v[46:47], 2, s[10:11]
	v_lshl_add_u64 v[50:51], v[50:51], 2, s[10:11]
	v_lshl_add_u64 v[30:31], v[30:31], 2, s[10:11]
	v_lshl_add_u64 v[32:33], v[32:33], 2, s[10:11]
	global_load_dword v154, v[28:29], off
	global_load_dword v155, v[44:45], off
	s_nop 0
	global_load_dword v44, v[50:51], off
	global_load_dword v45, v[32:33], off
	s_nop 0
	global_load_dword v50, v[30:31], off
	global_load_dword v51, v[26:27], off
	v_lshl_add_u64 v[26:27], v[48:49], 2, s[10:11]
	global_load_dword v46, v[46:47], off
	s_nop 0
	global_load_dword v47, v[26:27], off
	ds_write_b128 v139, v[22:25] offset:3072
	s_waitcnt vmcnt(10)
	v_cvt_pk_bf16_f32 v22, v54, v16
	v_cvt_pk_bf16_f32 v23, v21, v53
	s_waitcnt vmcnt(9)
	v_cvt_pk_bf16_f32 v24, v55, v52
	s_waitcnt vmcnt(8)
	v_cvt_pk_bf16_f32 v25, v56, v43
	v_add_u32_e32 v26, v35, v20
	v_add_u32_e32 v28, v36, v20
	v_add_u32_e32 v30, v37, v20
	v_add_u32_e32 v32, v38, v20
	v_add_u32_e32 v34, v39, v20
	v_add_u32_e32 v38, v41, v20
	v_add_u32_e32 v36, v40, v20
	v_add_u32_e32 v20, v42, v20
	v_ashrrev_i32_e32 v27, 31, v26
	v_ashrrev_i32_e32 v29, 31, v28
	v_ashrrev_i32_e32 v31, 31, v30
	v_ashrrev_i32_e32 v35, 31, v34
	v_ashrrev_i32_e32 v39, 31, v38
	v_ashrrev_i32_e32 v33, 31, v32
	v_ashrrev_i32_e32 v37, 31, v36
	v_ashrrev_i32_e32 v21, 31, v20
	v_lshl_add_u64 v[26:27], v[26:27], 2, s[10:11]
	v_lshl_add_u64 v[28:29], v[28:29], 2, s[10:11]
	v_lshl_add_u64 v[30:31], v[30:31], 2, s[10:11]
	v_lshl_add_u64 v[34:35], v[34:35], 2, s[10:11]
	ds_write_b128 v139, v[22:25] offset:7168
	v_lshl_add_u64 v[24:25], v[38:39], 2, s[10:11]
	v_lshl_add_u64 v[32:33], v[32:33], 2, s[10:11]
	v_lshl_add_u64 v[36:37], v[36:37], 2, s[10:11]
	v_lshl_add_u64 v[40:41], v[20:21], 2, s[10:11]
	s_waitcnt vmcnt(2)
	v_cvt_pk_bf16_f32 v20, v51, v154
	v_cvt_pk_bf16_f32 v21, v155, v50
	s_waitcnt vmcnt(1)
	v_cvt_pk_bf16_f32 v22, v46, v45
	s_waitcnt vmcnt(0)
	v_cvt_pk_bf16_f32 v23, v47, v44
	global_load_dword v16, v[28:29], off
	s_nop 0
	global_load_dword v28, v[30:31], off
	global_load_dword v29, v[40:41], off
	s_nop 0
	global_load_dword v30, v[36:37], off
	global_load_dword v31, v[32:33], off
	s_nop 0
	global_load_dword v26, v[26:27], off
	s_nop 0
	global_load_dword v27, v[34:35], off
	s_nop 0
	global_load_dword v24, v[24:25], off
	ds_write_b128 v139, v[20:23] offset:11264
	s_waitcnt vmcnt(2)
	v_cvt_pk_bf16_f32 v20, v26, v16
	v_cvt_pk_bf16_f32 v21, v28, v31
	s_waitcnt vmcnt(1)
	v_cvt_pk_bf16_f32 v22, v27, v30
	s_waitcnt vmcnt(0)
	v_cvt_pk_bf16_f32 v23, v24, v29
	ds_write_b128 v139, v[20:23] offset:15360
	s_waitcnt lgkmcnt(0)
	s_cbranch_vccnz .LBB0_550
; #define GAS __attribute__((address_space(1)))
; __device__ __forceinline__ void m1_phase(ArgP A, int layer, LAS unsigned char* lds, int tid, int lane, int wave, int bid, int G) {
;     ...
;     float p_mr[4], p_mk[4], p_mv[4], p_w0[4], p_a0[4], p_kk[4], p_ka[4], p_rk[4], p_lw[4], p_lb[4];
; #pragma unroll
;     for (int ct = 0; ct < 4; ++ct) { const int n = h * 64 + ct * 16 + c; p_mr[ct] = mu[n]; p_mk[ct] = mu[512 + n]; p_mv[ct] = mu[1024 + n]; p_w0[ct] = w0[n]; p_a0[ct] = a0[n];
;         p_kk[ct] = kk_[n]; p_ka[ct] = ka_[n]; p_rk[ct] = rk_[n]; p_lw[ct] = lnw[n]; p_lb[ct] = lnb[n]; }
;     for (int unit = bid; unit < 512 + 64; unit += G) {
;         const int tile = unit < 512 ? unit : 512 + ((unit - 512) >> 1); const int jlo = unit < 512 ? 0 : ((unit - 512) & 1) * 2, jhi = unit < 512 ? 4 : jlo + 2;
;         const int m0 = tile * 16;
;         f32x4 accw[4], acca[4], accg[4];
;         {
;             const int m = m0 + c; float msk; const GAS float* zr = Z + (size_t)m * NCP; const GAS float* pr = prev_row(Z, shift_st, m, msk);
;             float t[8]; bf16x8 aw, aa, ag[3];
;             zm8(zr, pr, msk, mu, 1536 + quad * 8, t);
	s_load_dwordx2 s[10:11], s[8:9], 0x138
	v_readlane_b32 s46, v254, 10
	v_readlane_b32 s47, v254, 11
	s_lshl_b32 s2, s14, 7
	s_mov_b32 s47, s83
	s_add_i32 s15, s2, 0
	s_lshl_b32 s0, s46, 9
	s_lshl_b64 s[12:13], s[46:47], 20
	s_lshl_b64 s[16:17], s[46:47], 2
	s_add_i32 s15, s15, 0x20000
	s_mul_i32 s82, s46, 0x6a0
	s_waitcnt lgkmcnt(0)
	s_add_u32 s18, s10, 0x22400000
	s_addc_u32 s19, s11, 0
	s_lshl_b64 s[2:3], s[82:83], 2
	s_mov_b32 s1, s83
	s_add_u32 s2, s40, s2
	s_addc_u32 s3, s41, s3
	s_lshl_b64 s[0:1], s[0:1], 2
	s_add_u32 s26, s44, s0
	s_addc_u32 s27, s45, s1
	s_add_u32 s28, s48, s0
	s_load_dwordx4 s[20:23], s[8:9], 0xc0
	s_load_dwordx2 s[24:25], s[8:9], 0xa8
	s_addc_u32 s29, s49, s1
	s_add_u32 s30, s52, s0
	s_addc_u32 s31, s53, s1
	s_add_u32 s36, s54, s0
	s_addc_u32 s37, s55, s1
	s_waitcnt lgkmcnt(0)
	s_add_u32 s24, s24, s0
	s_addc_u32 s25, s25, s1
	s_add_u32 s20, s20, s0
	s_addc_u32 s21, s21, s1
	v_lshlrev_b64 v[78:79], 2, v[74:75]
	s_add_u32 s0, s22, s0
	v_lshl_add_u64 v[20:21], s[2:3], 0, v[78:79]
	s_movk_i32 s5, 0x1000
	s_addc_u32 s1, s23, s1
	v_add_co_u32_e32 v22, vcc, s5, v20
	v_lshl_add_u64 v[24:25], s[26:27], 0, v[78:79]
	s_nop 0
	v_addc_co_u32_e32 v23, vcc, 0, v21, vcc
	v_lshl_add_u64 v[26:27], s[28:29], 0, v[78:79]
	v_lshl_add_u64 v[28:29], s[30:31], 0, v[78:79]
	v_lshl_add_u64 v[30:31], s[36:37], 0, v[78:79]
	v_lshl_add_u64 v[32:33], s[24:25], 0, v[78:79]
	v_lshl_add_u64 v[34:35], s[20:21], 0, v[78:79]
	v_lshl_add_u64 v[36:37], s[0:1], 0, v[78:79]
	global_load_dword v140, v[20:21], off
	global_load_dword v141, v[20:21], off offset:2048
	global_load_dword v142, v[20:21], off offset:64
	global_load_dword v143, v[20:21], off offset:2112
	global_load_dword v144, v[20:21], off offset:128
	global_load_dword v145, v[20:21], off offset:2176
	global_load_dword v146, v[20:21], off offset:2240
	global_load_dword v147, v[20:21], off offset:192
	global_load_dword v148, v[22:23], off
	global_load_dword v149, v[22:23], off offset:64
	global_load_dword v150, v[22:23], off offset:128
	global_load_dword v151, v[22:23], off offset:192
	global_load_dword v152, v[24:25], off
	global_load_dword v153, v[24:25], off offset:64
	global_load_dword v154, v[24:25], off offset:128
	global_load_dword v155, v[24:25], off offset:192
	global_load_dword v156, v[26:27], off
	global_load_dword v157, v[26:27], off offset:64
	global_load_dword v158, v[26:27], off offset:128
	global_load_dword v159, v[26:27], off offset:192
	global_load_dword v160, v[28:29], off
	global_load_dword v161, v[28:29], off offset:64
	global_load_dword v162, v[28:29], off offset:128
	global_load_dword v163, v[28:29], off offset:192
	global_load_dword v164, v[30:31], off
	global_load_dword v165, v[30:31], off offset:64
	global_load_dword v166, v[30:31], off offset:128
	global_load_dword v167, v[30:31], off offset:192
	global_load_dword v168, v[32:33], off
	global_load_dword v169, v[32:33], off offset:64
	global_load_dword v170, v[32:33], off offset:128
	global_load_dword v171, v[32:33], off offset:192
	global_load_dword v172, v[34:35], off
	global_load_dword v173, v[34:35], off offset:64
	global_load_dword v174, v[34:35], off offset:128
	global_load_dword v175, v[34:35], off offset:192
	global_load_dword v176, v[36:37], off
	global_load_dword v177, v[36:37], off offset:64
	global_load_dword v190, v[36:37], off offset:128
	global_load_dword v191, v[36:37], off offset:192
	s_load_dwordx2 s[0:1], s[8:9], 0x18
	s_add_u32 s26, s10, 0xfa80000
	s_addc_u32 s27, s11, 0
	s_add_u32 s28, s10, 0x25700000
	s_mul_i32 s5, s46, 0xd4000
	s_addc_u32 s29, s11, 0
	v_lshlrev_b32_e32 v16, 3, v19
	v_and_b32_e32 v20, 3, v18
	s_waitcnt lgkmcnt(0)
	s_add_u32 s38, s0, s5
	v_cmp_ne_u32_e64 s[40:41], 0, v20
	v_or_b32_e32 v20, 0x600, v16
	s_addc_u32 s39, s1, 0
	s_ashr_i32 s5, s4, 31
	v_or_b32_e32 v22, 0x620, v16
	v_or_b32_e32 v24, 0x640, v16
	v_or_b32_e32 v26, 0x660, v16
	v_or_b32_e32 v28, 0x680, v16
	v_lshlrev_b32_e32 v16, 2, v20
	s_lshl_b64 s[0:1], s[4:5], 2
	v_lshl_add_u64 v[80:81], s[2:3], 0, v[16:17]
	v_lshlrev_b32_e32 v16, 2, v22
	s_add_u32 s0, s10, s0
	v_lshl_add_u64 v[82:83], s[2:3], 0, v[16:17]
	v_lshlrev_b32_e32 v16, 2, v138
	s_addc_u32 s1, s11, s1
	v_lshl_add_u64 v[30:31], s[0:1], 0, v[16:17]
	s_mov_b64 s[0:1], 0x24600000
	v_lshl_add_u64 v[84:85], v[30:31], 0, s[0:1]
	s_mov_b64 s[0:1], 0x1ad00000
	v_lshlrev_b32_e32 v192, 2, v19
	v_lshlrev_b32_e32 v193, 5, v19
	v_lshl_add_u64 v[86:87], v[30:31], 0, s[0:1]
	s_mov_b32 s0, s46
	v_ashrrev_i32_e32 v19, 31, v18
	s_movk_i32 s20, 0x6a0
	v_writelane_b32 v254, s0, 10
	v_lshlrev_b64 v[96:97], 2, v[18:19]
	v_cmp_gt_i32_e64 s[44:45], s20, v18
	v_writelane_b32 v254, s1, 11
	v_add_u32_e32 v199, 0xfffffe00, v18
	v_lshl_add_u64 v[18:19], s[10:11], 0, v[96:97]
	s_mov_b64 s[0:1], 0xfa8fc00
	v_lshl_add_u64 v[98:99], v[18:19], 0, s[0:1]
	s_mov_b64 s[0:1], 0xfaa4c00
	v_or_b32_e32 v194, 1, v192
	v_lshl_add_u64 v[100:101], v[18:19], 0, s[0:1]
	s_mov_b64 s[0:1], 0xfab9c00
	v_lshlrev_b32_e32 v21, 3, v194
	v_or_b32_e32 v196, 2, v192
	v_lshl_add_u64 v[102:103], v[18:19], 0, s[0:1]
	s_mov_b64 s[0:1], 0xfacec00
	v_lshlrev_b32_e32 v23, 3, v196
	v_or_b32_e32 v198, 3, v192
	v_lshlrev_b32_e32 v16, 2, v24
	v_lshl_add_u64 v[104:105], v[18:19], 0, s[0:1]
	v_add_u32_e32 v18, 0, v21
	v_lshlrev_b32_e32 v25, 3, v198
	v_lshl_add_u64 v[88:89], s[2:3], 0, v[16:17]
	v_lshlrev_b32_e32 v16, 2, v26
	v_add_u32_e32 v200, 0x20000, v18
	v_add_u32_e32 v18, 0, v23
	v_lshl_add_u64 v[90:91], s[2:3], 0, v[16:17]
	v_lshlrev_b32_e32 v16, 2, v28
	v_add_u32_e32 v201, 0x20000, v18
	v_add_u32_e32 v18, 0, v25
	s_mov_b32 s30, 0xbfb8aa3b
	s_movk_i32 s36, 0x2000
	v_cmp_eq_u32_e64 s[42:43], 0, v138
	v_lshl_add_u64 v[92:93], s[2:3], 0, v[16:17]
	v_lshl_add_u64 v[94:95], s[26:27], 0, v[78:79]
	s_lshl_b32 s22, s46, 7
	v_lshlrev_b32_e32 v16, 2, v20
	v_lshlrev_b32_e32 v106, 2, v22
	v_lshlrev_b32_e32 v108, 2, v24
	v_lshlrev_b32_e32 v110, 2, v26
	v_lshlrev_b32_e32 v112, 2, v28
	v_add_u32_e32 v202, 0x20000, v18
	s_mov_b32 s23, s70
	s_movk_i32 s31, 0x5400
	s_movk_i32 s33, 0x1a80
	s_mov_b32 s37, 0x3f200000
	s_mov_b64 s[48:49], 0x800
	s_branch .LBB0_297

; __device__ __forceinline__ bf16x8 pack8(const float (&t)[8]) { u32x4 w; w.x = pk2(t[0], t[1]); w.y = pk2(t[2], t[3]); w.z = pk2(t[4], t[5]); w.w = pk2(t[6], t[7]); return __builtin_bit_cast(bf16x8, w); }
; __device__ __forceinline__ void m3_phase(ArgP A, int layer, LAS unsigned char* lds, int tid, int lane, int wave, int bid, int G) {
;     ...
;     const int j = tid, wv = wave, hh = j >> 7, c = lane & 15, quad = lane >> 4, g = wv >> 1, colbase = (wv & 1) * 64;
;     const int win = 2 << hh; const float inv_full = 1.0f / (float)win;
;     const float gnw_j = gnw[j], gnb_j = gnb[j];
;     bf16x8 bp[4][4];
; #pragma unroll
;     for (int ct = 0; ct < 4; ++ct)
; #pragma unroll
;         for (int kk = 0; kk < 4; ++kk) { float tb[8];
; #pragma unroll
;             for (int jj = 0; jj < 8; ++jj) tb[jj] = pw[(size_t)(g * 128 + kk * 32 + quad * 8 + jj) * 128 + colbase + ct * 16 + c];
;             bp[kk][ct] = pack8(tb); }
.LBB0_777:
	s_cmp_le_i32 s74, s18
	s_cselect_b64 s[16:17], -1, 0
	s_and_b64 s[0:1], s[16:17], s[4:5]
	s_andn2_b64 vcc, exec, s[0:1]
	s_cbranch_vccnz .LBB0_1341
	s_waitcnt vmcnt(0)
	v_mov_b32_e32 v90, v195
	s_mov_b64 s[18:19], s[68:69]
	v_readfirstlane_b32 s0, v90
	v_bfe_u32 v94, v90, 4, 2
	s_and_b32 s2, s0, 0xffffff80
	s_waitcnt vmcnt(0)
	v_lshl_or_b32 v4, v94, 3, s2
	v_or_b32_e32 v10, 3, v4
	v_ashrrev_i32_e32 v11, 31, v10
	v_lshlrev_b64 v[12:13], 9, v[10:11]
	v_or_b32_e32 v10, 4, v4
	v_ashrrev_i32_e32 v11, 31, v10
	v_lshlrev_b64 v[14:15], 9, v[10:11]
	v_or_b32_e32 v10, 5, v4
	v_ashrrev_i32_e32 v11, 31, v10
	v_lshlrev_b64 v[18:19], 9, v[10:11]
	v_or_b32_e32 v10, 6, v4
	v_ashrrev_i32_e32 v11, 31, v10
	v_lshlrev_b64 v[20:21], 9, v[10:11]
	v_or_b32_e32 v10, 7, v4
	v_ashrrev_i32_e32 v11, 31, v10
	v_lshlrev_b64 v[66:67], 9, v[10:11]
	v_or_b32_e32 v10, 32, v4
	v_ashrrev_i32_e32 v11, 31, v10
	v_lshlrev_b64 v[22:23], 9, v[10:11]
	v_or_b32_e32 v10, 33, v4
	v_ashrrev_i32_e32 v11, 31, v10
	v_lshlrev_b64 v[24:25], 9, v[10:11]
	v_or_b32_e32 v10, 34, v4
	v_ashrrev_i32_e32 v11, 31, v10
	v_lshlrev_b64 v[56:57], 9, v[10:11]
	v_or_b32_e32 v10, 35, v4
	v_ashrrev_i32_e32 v11, 31, v10
	v_lshlrev_b64 v[58:59], 9, v[10:11]
	v_or_b32_e32 v10, 36, v4
	v_ashrrev_i32_e32 v11, 31, v10
	v_lshlrev_b64 v[60:61], 9, v[10:11]
	v_or_b32_e32 v10, 37, v4
	v_ashrrev_i32_e32 v11, 31, v10
	v_lshlrev_b64 v[62:63], 9, v[10:11]
	v_or_b32_e32 v10, 38, v4
	v_ashrrev_i32_e32 v11, 31, v10
	v_lshlrev_b64 v[64:65], 9, v[10:11]
	v_or_b32_e32 v10, 39, v4
	v_ashrrev_i32_e32 v11, 31, v10
	v_lshlrev_b64 v[68:69], 9, v[10:11]
	v_or_b32_e32 v10, 64, v4
	v_ashrrev_i32_e32 v11, 31, v10
	v_lshlrev_b64 v[26:27], 9, v[10:11]
	v_or_b32_e32 v10, 0x41, v4
	v_ashrrev_i32_e32 v11, 31, v10
	v_lshlrev_b64 v[28:29], 9, v[10:11]
	v_or_b32_e32 v10, 0x42, v4
	v_ashrrev_i32_e32 v11, 31, v10
	v_lshlrev_b64 v[44:45], 9, v[10:11]
	v_or_b32_e32 v10, 0x43, v4
	v_ashrrev_i32_e32 v11, 31, v10
	v_lshlrev_b64 v[46:47], 9, v[10:11]
	v_or_b32_e32 v10, 0x44, v4
	v_ashrrev_i32_e32 v11, 31, v10
	v_lshlrev_b64 v[48:49], 9, v[10:11]
	v_or_b32_e32 v10, 0x45, v4
	v_ashrrev_i32_e32 v11, 31, v10
	v_lshlrev_b64 v[50:51], 9, v[10:11]
	v_or_b32_e32 v10, 0x46, v4
	s_load_dwordx4 s[4:7], s[18:19], 0xb0
	v_ashrrev_i32_e32 v11, 31, v10
	v_readlane_b32 s14, v254, 10
	v_lshlrev_b64 v[52:53], 9, v[10:11]
	v_or_b32_e32 v10, 0x47, v4
	s_lshl_b32 s82, s14, 9
	v_ashrrev_i32_e32 v11, 31, v10
	s_and_b32 s1, s0, 64
	v_lshlrev_b64 v[54:55], 9, v[10:11]
	v_or_b32_e32 v10, 0x61, v4
	s_lshl_b64 s[8:9], s[82:83], 2
	v_ashrrev_i32_e32 v11, 31, v10
	s_waitcnt lgkmcnt(0)
	s_add_u32 s10, s4, s8
	v_lshlrev_b64 v[30:31], 9, v[10:11]
	v_or_b32_e32 v10, 0x62, v4
	s_addc_u32 s11, s5, s9
	v_ashrrev_i32_e32 v11, 31, v10
	s_add_u32 s12, s6, s8
	v_lshlrev_b64 v[32:33], 9, v[10:11]
	v_or_b32_e32 v10, 0x63, v4
	s_addc_u32 s13, s7, s9
	s_load_dwordx4 s[4:7], s[18:19], 0xf0
	v_readlane_b32 s15, v254, 11
	v_ashrrev_i32_e32 v11, 31, v10
	s_mov_b32 s15, s83
	v_lshlrev_b64 v[34:35], 9, v[10:11]
	v_or_b32_e32 v10, 0x64, v4
	v_ashrrev_i32_e32 v11, 31, v10
	v_writelane_b32 v254, s14, 10
	v_lshlrev_b64 v[36:37], 9, v[10:11]
	v_or_b32_e32 v10, 0x65, v4
	v_writelane_b32 v254, s15, 11
	s_lshl_b64 s[14:15], s[14:15], 18
	v_ashrrev_i32_e32 v5, 31, v4
	v_ashrrev_i32_e32 v11, 31, v10
	s_waitcnt lgkmcnt(0)
	s_add_u32 s3, s6, s14
	v_ashrrev_i32_e32 v91, 31, v90
	v_or_b32_e32 v0, 0x60, v4
	v_lshlrev_b64 v[2:3], 9, v[4:5]
	v_or_b32_e32 v6, 1, v4
	v_or_b32_e32 v8, 2, v4
	v_lshlrev_b64 v[38:39], 9, v[10:11]
	v_or_b32_e32 v10, 0x66, v4
	v_or_b32_e32 v4, 0x67, v4
	s_addc_u32 s7, s7, s15
	s_lshl_b32 s6, s1, 2
	v_and_b32_e32 v122, 15, v90
	v_ashrrev_i32_e32 v5, 31, v4
	v_lshlrev_b64 v[92:93], 2, v[90:91]
	s_add_u32 s6, s3, s6
	v_lshlrev_b64 v[42:43], 9, v[4:5]
	v_lshl_add_u64 v[4:5], s[10:11], 0, v[92:93]
	s_addc_u32 s7, s7, 0
	v_lshlrev_b32_e32 v16, 2, v122
	v_ashrrev_i32_e32 v7, 31, v6
	v_ashrrev_i32_e32 v9, 31, v8
	global_load_dword v95, v[4:5], off
	v_lshl_add_u64 v[4:5], s[12:13], 0, v[92:93]
	v_lshl_add_u64 v[120:121], s[6:7], 0, v[16:17]
	v_lshlrev_b64 v[6:7], 9, v[6:7]
	v_lshlrev_b64 v[8:9], 9, v[8:9]
	v_ashrrev_i32_e32 v11, 31, v10
	global_load_dword v168, v[4:5], off
	v_lshl_add_u64 v[4:5], v[120:121], 0, v[2:3]
	v_lshlrev_b64 v[40:41], 9, v[10:11]
	v_lshl_add_u64 v[10:11], v[120:121], 0, v[6:7]
	v_lshl_add_u64 v[6:7], v[120:121], 0, v[8:9]
	v_lshl_add_u64 v[12:13], v[120:121], 0, v[12:13]
	v_lshl_add_u64 v[8:9], v[120:121], 0, v[14:15]
	v_lshl_add_u64 v[14:15], v[120:121], 0, v[18:19]
	v_lshl_add_u64 v[2:3], v[120:121], 0, v[20:21]
	v_lshl_add_u64 v[66:67], v[120:121], 0, v[66:67]
	global_load_dword v16, v[4:5], off
	global_load_dword v18, v[10:11], off
	global_load_dword v19, v[12:13], off
	global_load_dword v20, v[6:7], off
	global_load_dword v21, v[14:15], off
	global_load_dword v70, v[8:9], off
	global_load_dword v71, v[66:67], off
	global_load_dword v72, v[2:3], off
	v_lshl_add_u64 v[78:79], v[120:121], 0, v[24:25]
	s_waitcnt vmcnt(6)
	v_cvt_pk_bf16_f32 v18, v16, v18
	s_waitcnt vmcnt(4)
	v_cvt_pk_bf16_f32 v19, v20, v19
	s_waitcnt vmcnt(2)
	v_cvt_pk_bf16_f32 v20, v70, v21
	s_waitcnt vmcnt(0)
	v_cvt_pk_bf16_f32 v21, v72, v71
	v_lshl_add_u64 v[72:73], v[120:121], 0, v[22:23]
	v_lshl_add_u64 v[74:75], v[120:121], 0, v[56:57]
	v_lshl_add_u64 v[80:81], v[120:121], 0, v[58:59]
	v_lshl_add_u64 v[76:77], v[120:121], 0, v[60:61]
	v_lshl_add_u64 v[82:83], v[120:121], 0, v[62:63]
	v_lshl_add_u64 v[70:71], v[120:121], 0, v[64:65]
	v_lshl_add_u64 v[84:85], v[120:121], 0, v[68:69]
	global_load_dword v16, v[78:79], off
	global_load_dword v22, v[72:73], off
	global_load_dword v23, v[80:81], off
	global_load_dword v24, v[74:75], off
	global_load_dword v25, v[82:83], off
	global_load_dword v56, v[76:77], off
	global_load_dword v57, v[84:85], off
	global_load_dword v58, v[70:71], off
	v_lshl_add_u64 v[100:101], v[120:121], 0, v[28:29]
	s_waitcnt vmcnt(6)
; __device__ __forceinline__ bf16x8 pack8(const float (&t)[8]) { u32x4 w; w.x = pk2(t[0], t[1]); w.y = pk2(t[2], t[3]); w.z = pk2(t[4], t[5]); w.w = pk2(t[6], t[7]); return __builtin_bit_cast(bf16x8, w); }
; __device__ __forceinline__ void m3_phase(ArgP A, int layer, LAS unsigned char* lds, int tid, int lane, int wave, int bid, int G) {
;     ...
;     bf16x8 bp[4][4];
; #pragma unroll
;     for (int ct = 0; ct < 4; ++ct)
; #pragma unroll
;         for (int kk = 0; kk < 4; ++kk) { float tb[8];
; #pragma unroll
;             for (int jj = 0; jj < 8; ++jj) tb[jj] = pw[(size_t)(g * 128 + kk * 32 + quad * 8 + jj) * 128 + colbase + ct * 16 + c];
;             bp[kk][ct] = pack8(tb); }
	v_cvt_pk_bf16_f32 v22, v22, v16
	s_waitcnt vmcnt(4)
	v_cvt_pk_bf16_f32 v23, v24, v23
	s_waitcnt vmcnt(2)
	v_cvt_pk_bf16_f32 v24, v56, v25
	s_waitcnt vmcnt(0)
	v_cvt_pk_bf16_f32 v25, v58, v57
	v_lshl_add_u64 v[88:89], v[120:121], 0, v[26:27]
	v_lshl_add_u64 v[96:97], v[120:121], 0, v[44:45]
	v_lshl_add_u64 v[102:103], v[120:121], 0, v[46:47]
	v_lshl_add_u64 v[98:99], v[120:121], 0, v[48:49]
	v_lshl_add_u64 v[104:105], v[120:121], 0, v[50:51]
	v_lshl_add_u64 v[86:87], v[120:121], 0, v[52:53]
	v_lshl_add_u64 v[106:107], v[120:121], 0, v[54:55]
	global_load_dword v16, v[100:101], off
	global_load_dword v26, v[88:89], off
	global_load_dword v27, v[102:103], off
	global_load_dword v28, v[96:97], off
	global_load_dword v29, v[104:105], off
	global_load_dword v44, v[98:99], off
	global_load_dword v45, v[106:107], off
	global_load_dword v46, v[86:87], off
	v_ashrrev_i32_e32 v1, 31, v0
	v_lshlrev_b64 v[0:1], 9, v[0:1]
	v_lshl_add_u64 v[114:115], v[120:121], 0, v[30:31]
	s_waitcnt vmcnt(6)
	v_cvt_pk_bf16_f32 v26, v26, v16
	s_waitcnt vmcnt(4)
	v_cvt_pk_bf16_f32 v27, v28, v27
	s_waitcnt vmcnt(2)
	v_cvt_pk_bf16_f32 v28, v44, v29
	s_waitcnt vmcnt(0)
	v_cvt_pk_bf16_f32 v29, v46, v45
	v_lshl_add_u64 v[108:109], v[120:121], 0, v[0:1]
	v_lshl_add_u64 v[110:111], v[120:121], 0, v[32:33]
	v_lshl_add_u64 v[116:117], v[120:121], 0, v[34:35]
	v_lshl_add_u64 v[112:113], v[120:121], 0, v[36:37]
	v_lshl_add_u64 v[118:119], v[120:121], 0, v[38:39]
	v_lshl_add_u64 v[0:1], v[120:121], 0, v[40:41]
	v_lshl_add_u64 v[120:121], v[120:121], 0, v[42:43]
	global_load_dword v16, v[114:115], off
	global_load_dword v30, v[108:109], off
	global_load_dword v31, v[116:117], off
	global_load_dword v32, v[110:111], off
	global_load_dword v33, v[118:119], off
	global_load_dword v34, v[112:113], off
	global_load_dword v35, v[120:121], off
	global_load_dword v36, v[0:1], off
	global_load_dword v145, v[10:11], off offset:64
	global_load_dword v146, v[4:5], off offset:64
	global_load_dword v147, v[12:13], off offset:64
	global_load_dword v148, v[6:7], off offset:64
	global_load_dword v37, v[14:15], off offset:64
	global_load_dword v38, v[8:9], off offset:64
	global_load_dword v39, v[66:67], off offset:64
	global_load_dword v40, v[2:3], off offset:64
	s_waitcnt vmcnt(14)
	v_cvt_pk_bf16_f32 v30, v30, v16
	s_waitcnt vmcnt(12)
	v_cvt_pk_bf16_f32 v31, v32, v31
	s_waitcnt vmcnt(10)
	v_cvt_pk_bf16_f32 v32, v34, v33
	s_waitcnt vmcnt(8)
	v_cvt_pk_bf16_f32 v33, v36, v35
	global_load_dword v16, v[78:79], off offset:64
	global_load_dword v149, v[72:73], off offset:64
	global_load_dword v150, v[80:81], off offset:64
	global_load_dword v151, v[74:75], off offset:64
	global_load_dword v41, v[82:83], off offset:64
	global_load_dword v42, v[76:77], off offset:64
	global_load_dword v43, v[84:85], off offset:64
	global_load_dword v44, v[70:71], off offset:64
	s_waitcnt vmcnt(14)
	v_cvt_pk_bf16_f32 v34, v146, v145
	s_waitcnt vmcnt(12)
	v_cvt_pk_bf16_f32 v35, v148, v147
	s_waitcnt vmcnt(10)
	v_cvt_pk_bf16_f32 v36, v38, v37
	s_waitcnt vmcnt(8)
	v_cvt_pk_bf16_f32 v37, v40, v39
	global_load_dword v152, v[100:101], off offset:64
	global_load_dword v153, v[88:89], off offset:64
	global_load_dword v145, v[102:103], off offset:64
	global_load_dword v146, v[96:97], off offset:64
	global_load_dword v45, v[104:105], off offset:64
	global_load_dword v46, v[98:99], off offset:64
	global_load_dword v47, v[106:107], off offset:64
	global_load_dword v48, v[86:87], off offset:64
	s_waitcnt vmcnt(14)
	v_cvt_pk_bf16_f32 v38, v149, v16
	s_waitcnt vmcnt(12)
	v_cvt_pk_bf16_f32 v39, v151, v150
	s_waitcnt vmcnt(10)
	v_cvt_pk_bf16_f32 v40, v42, v41
	s_waitcnt vmcnt(8)
	v_cvt_pk_bf16_f32 v41, v44, v43
	global_load_dword v16, v[114:115], off offset:64
	global_load_dword v147, v[108:109], off offset:64
	global_load_dword v148, v[116:117], off offset:64
	global_load_dword v149, v[110:111], off offset:64
	global_load_dword v49, v[118:119], off offset:64
	global_load_dword v50, v[112:113], off offset:64
	global_load_dword v51, v[120:121], off offset:64
	global_load_dword v52, v[0:1], off offset:64
	s_waitcnt vmcnt(14)
	v_cvt_pk_bf16_f32 v42, v153, v152
	s_waitcnt vmcnt(12)
	v_cvt_pk_bf16_f32 v43, v146, v145
	s_waitcnt vmcnt(10)
	v_cvt_pk_bf16_f32 v44, v46, v45
	s_waitcnt vmcnt(8)
	v_cvt_pk_bf16_f32 v45, v48, v47
	global_load_dword v150, v[10:11], off offset:128
	global_load_dword v151, v[4:5], off offset:128
	global_load_dword v152, v[12:13], off offset:128
	global_load_dword v153, v[6:7], off offset:128
	global_load_dword v53, v[14:15], off offset:128
	global_load_dword v54, v[8:9], off offset:128
	global_load_dword v55, v[66:67], off offset:128
	global_load_dword v56, v[2:3], off offset:128
	s_waitcnt vmcnt(14)
	v_cvt_pk_bf16_f32 v46, v147, v16
	s_waitcnt vmcnt(12)
	v_cvt_pk_bf16_f32 v47, v149, v148
	s_waitcnt vmcnt(10)
	v_cvt_pk_bf16_f32 v48, v50, v49
	s_waitcnt vmcnt(8)
	v_cvt_pk_bf16_f32 v49, v52, v51
	global_load_dword v16, v[78:79], off offset:128
	global_load_dword v145, v[72:73], off offset:128
	global_load_dword v146, v[80:81], off offset:128
	global_load_dword v147, v[74:75], off offset:128
	global_load_dword v57, v[82:83], off offset:128
	global_load_dword v58, v[76:77], off offset:128
	global_load_dword v59, v[84:85], off offset:128
	global_load_dword v60, v[70:71], off offset:128
	s_waitcnt vmcnt(14)
	v_cvt_pk_bf16_f32 v50, v151, v150
	s_waitcnt vmcnt(12)
	v_cvt_pk_bf16_f32 v51, v153, v152
	s_waitcnt vmcnt(10)
	v_cvt_pk_bf16_f32 v52, v54, v53
	s_waitcnt vmcnt(8)
; __device__ __forceinline__ bf16x8 pack8(const float (&t)[8]) { u32x4 w; w.x = pk2(t[0], t[1]); w.y = pk2(t[2], t[3]); w.z = pk2(t[4], t[5]); w.w = pk2(t[6], t[7]); return __builtin_bit_cast(bf16x8, w); }
; __device__ __forceinline__ void m3_phase(ArgP A, int layer, LAS unsigned char* lds, int tid, int lane, int wave, int bid, int G) {
;     ...
;     bf16x8 bp[4][4];
; #pragma unroll
;     for (int ct = 0; ct < 4; ++ct)
; #pragma unroll
;         for (int kk = 0; kk < 4; ++kk) { float tb[8];
; #pragma unroll
;             for (int jj = 0; jj < 8; ++jj) tb[jj] = pw[(size_t)(g * 128 + kk * 32 + quad * 8 + jj) * 128 + colbase + ct * 16 + c];
;             bp[kk][ct] = pack8(tb); }
	v_cvt_pk_bf16_f32 v53, v56, v55
	global_load_dword v148, v[100:101], off offset:128
	global_load_dword v149, v[88:89], off offset:128
	global_load_dword v150, v[102:103], off offset:128
	global_load_dword v151, v[96:97], off offset:128
	global_load_dword v61, v[104:105], off offset:128
	global_load_dword v62, v[98:99], off offset:128
	global_load_dword v63, v[106:107], off offset:128
	global_load_dword v64, v[86:87], off offset:128
	s_waitcnt vmcnt(14)
	v_cvt_pk_bf16_f32 v54, v145, v16
	s_waitcnt vmcnt(12)
	v_cvt_pk_bf16_f32 v55, v147, v146
	s_waitcnt vmcnt(10)
	v_cvt_pk_bf16_f32 v56, v58, v57
	s_waitcnt vmcnt(8)
	v_cvt_pk_bf16_f32 v57, v60, v59
	global_load_dword v16, v[114:115], off offset:128
	global_load_dword v152, v[108:109], off offset:128
	global_load_dword v153, v[116:117], off offset:128
	global_load_dword v145, v[110:111], off offset:128
	global_load_dword v65, v[118:119], off offset:128
	global_load_dword v68, v[112:113], off offset:128
	global_load_dword v69, v[120:121], off offset:128
	global_load_dword v123, v[0:1], off offset:128
	s_waitcnt vmcnt(14)
	v_cvt_pk_bf16_f32 v58, v149, v148
	s_waitcnt vmcnt(12)
	v_cvt_pk_bf16_f32 v59, v151, v150
	s_waitcnt vmcnt(10)
	v_cvt_pk_bf16_f32 v60, v62, v61
	s_waitcnt vmcnt(8)
	v_cvt_pk_bf16_f32 v61, v64, v63
	global_load_dword v10, v[10:11], off offset:192
	s_nop 0
	global_load_dword v4, v[4:5], off offset:192
	s_nop 0
	global_load_dword v5, v[12:13], off offset:192
	s_nop 0
	global_load_dword v6, v[6:7], off offset:192
	s_nop 0
	global_load_dword v7, v[14:15], off offset:192
	s_nop 0
	global_load_dword v8, v[8:9], off offset:192
	s_nop 0
	global_load_dword v9, v[66:67], off offset:192
	s_nop 0
	global_load_dword v2, v[2:3], off offset:192
	s_waitcnt vmcnt(14)
	v_cvt_pk_bf16_f32 v62, v152, v16
	s_waitcnt vmcnt(12)
	v_cvt_pk_bf16_f32 v63, v145, v153
	s_waitcnt vmcnt(10)
	v_cvt_pk_bf16_f32 v64, v68, v65
	s_waitcnt vmcnt(8)
	v_cvt_pk_bf16_f32 v65, v123, v69
	global_load_dword v146, v[78:79], off offset:192
	global_load_dword v3, v[72:73], off offset:192
	global_load_dword v147, v[80:81], off offset:192
	global_load_dword v148, v[74:75], off offset:192
	global_load_dword v149, v[82:83], off offset:192
	global_load_dword v150, v[76:77], off offset:192
	global_load_dword v151, v[84:85], off offset:192
	global_load_dword v152, v[70:71], off offset:192
	s_waitcnt vmcnt(14)
	v_cvt_pk_bf16_f32 v66, v4, v10
	s_waitcnt vmcnt(12)
	v_cvt_pk_bf16_f32 v67, v6, v5
	s_waitcnt vmcnt(10)
	v_cvt_pk_bf16_f32 v68, v8, v7
	s_waitcnt vmcnt(8)
	v_cvt_pk_bf16_f32 v69, v2, v9
	global_load_dword v2, v[100:101], off offset:192
	global_load_dword v153, v[88:89], off offset:192
	global_load_dword v4, v[102:103], off offset:192
	global_load_dword v5, v[96:97], off offset:192
	global_load_dword v6, v[104:105], off offset:192
	global_load_dword v7, v[98:99], off offset:192
	global_load_dword v8, v[106:107], off offset:192
	global_load_dword v9, v[86:87], off offset:192
	s_waitcnt vmcnt(14)
	v_cvt_pk_bf16_f32 v70, v3, v146
	s_waitcnt vmcnt(12)
	v_cvt_pk_bf16_f32 v71, v148, v147
	s_waitcnt vmcnt(10)
	v_cvt_pk_bf16_f32 v72, v150, v149
	s_waitcnt vmcnt(8)
	v_cvt_pk_bf16_f32 v73, v152, v151
	global_load_dword v145, v[114:115], off offset:192
	global_load_dword v3, v[108:109], off offset:192
	global_load_dword v146, v[116:117], off offset:192
	global_load_dword v147, v[110:111], off offset:192
	global_load_dword v148, v[118:119], off offset:192
	global_load_dword v149, v[112:113], off offset:192
	global_load_dword v150, v[120:121], off offset:192
	s_nop 0
	global_load_dword v0, v[0:1], off offset:192
	s_waitcnt vmcnt(14)
	v_cvt_pk_bf16_f32 v74, v153, v2
	s_waitcnt vmcnt(12)
	v_cvt_pk_bf16_f32 v75, v5, v4
	s_waitcnt vmcnt(10)
	v_cvt_pk_bf16_f32 v76, v7, v6
	s_waitcnt vmcnt(8)
	v_cvt_pk_bf16_f32 v77, v9, v8
	v_readlane_b32 s6, v252, 21
	v_readlane_b32 s7, v252, 22
	s_andn2_b64 vcc, exec, s[6:7]
	s_waitcnt vmcnt(6)
	v_cvt_pk_bf16_f32 v78, v3, v145
	s_waitcnt vmcnt(4)
	v_cvt_pk_bf16_f32 v79, v147, v146
	s_waitcnt vmcnt(2)
	v_cvt_pk_bf16_f32 v80, v149, v148
	s_waitcnt vmcnt(0)
	v_cvt_pk_bf16_f32 v81, v0, v150
	s_cbranch_vccnz .LBB0_1341
; #define LAS __attribute__((address_space(3)))
; template <int T> __device__ __forceinline__ void pool_window(const float (&hv)[15], const float (&zv)[T], int win, float inv_full, bool zero_hist, int tq0, LAS float* DT, int trow0, int j) {
;     float P[16 + T]; P[0] = 0.f;
; #pragma unroll
;     for (int i = 0; i < 15; ++i) P[i + 1] = P[i] + hv[i];
; #pragma unroll
;     for (int t = 0; t < T; ++t) P[16 + t] = P[15 + t] + zv[t];
; #pragma unroll
;     for (int t = 0; t < T; ++t) { float lo = P[14 + t];
;         if (win == 4) lo = P[12 + t]; else if (win == 8) lo = P[8 + t]; else if (win == 16) lo = P[t];
;         float inv = inv_full; if (zero_hist) { const int n = tq0 + t + 1; inv = (n < win) ? 1.0f / (float)n : inv_full; }
;         DT[(trow0 + t) * 512 + j] = (P[16 + t] - lo) * inv - zv[t]; }
; __device__ __forceinline__ void m3_phase(ArgP A, int layer, LAS unsigned char* lds, int tid, int lane, int wave, int bid, int G) {
;     ...
;     const int j = tid, wv = wave, hh = j >> 7, c = lane & 15, quad = lane >> 4, g = wv >> 1, colbase = (wv & 1) * 64;
;     const int win = 2 << hh; const float inv_full = 1.0f / (float)win;
	v_ashrrev_i32_e32 v0, 7, v90
	v_lshlrev_b32_e64 v169, v0, 2
	v_cvt_f32_i32_e32 v0, v169
	v_writelane_b32 v254, s16, 18
	s_ashr_i32 s12, s0, 6
	s_lshl_b32 s0, s0, 2
	v_writelane_b32 v254, s17, 19
	v_div_scale_f32 v2, s[6:7], v0, v0, 1.0
	v_readlane_b32 s20, v254, 10
	v_readlane_b32 s21, v254, 11
	s_lshl_b64 s[6:7], s[20:21], 2
	v_writelane_b32 v254, s6, 20
	v_rcp_f32_e32 v3, v2
	s_and_b32 s0, s0, 0xfffffe00
	v_writelane_b32 v254, s7, 21
	v_cmp_lt_i32_e64 s[6:7], 2, v169
	v_fma_f32 v4, -v2, v3, 1.0
	v_fmac_f32_e32 v3, v4, v3
	v_writelane_b32 v254, s6, 22
	v_div_scale_f32 v4, vcc, 1.0, v0, 1.0
	s_nop 0
	v_writelane_b32 v254, s7, 23
	v_cmp_lt_i32_e64 s[6:7], 3, v169
	v_mul_f32_e32 v5, v4, v3
	v_fma_f32 v6, -v2, v5, v4
	v_writelane_b32 v254, s6, 24
	v_fmac_f32_e32 v5, v6, v3
	v_fma_f32 v2, -v2, v5, v4
	v_writelane_b32 v254, s7, 25
	v_cmp_lt_i32_e64 s[6:7], 4, v169
	v_div_fmas_f32 v2, v2, v3, v5
	v_div_fixup_f32 v170, v2, v0, 1.0
	v_writelane_b32 v254, s6, 26
	v_or_b32_e32 v0, s2, v122
	s_load_dwordx2 s[2:3], s[18:19], 0x138
	s_load_dwordx2 s[14:15], s[18:19], 0x100
	v_writelane_b32 v254, s7, 27
	v_cmp_lt_i32_e64 s[6:7], 5, v169
	s_add_i32 s0, s0, 0
	v_lshl_add_u32 v12, v122, 11, s0
	v_writelane_b32 v254, s6, 28
	s_lshl_b32 s0, s12, 2
	v_or_b32_e32 v0, s1, v0
	v_writelane_b32 v254, s7, 29
	v_cmp_lt_i32_e64 s[6:7], 6, v169
	s_add_i32 s31, s0, 0
	s_and_b32 s1, s0, -8
	v_writelane_b32 v254, s6, 30
	s_or_b32 s0, s0, 4
	s_lshl_b64 s[10:11], s[20:21], 16
	v_writelane_b32 v254, s7, 31
	v_cmp_lt_i32_e64 s[6:7], 7, v169
	s_add_i32 s1, s1, 0
	s_add_i32 s0, s0, 0
	v_writelane_b32 v254, s6, 32
	s_waitcnt lgkmcnt(0)
	s_add_u32 s33, s2, 0xfa80000
	s_addc_u32 s90, s3, 0
	v_writelane_b32 v254, s7, 33
	v_cmp_lt_i32_e64 s[6:7], 8, v169
	s_add_u32 s91, s2, 0x22400000
	s_addc_u32 s40, s3, 0
	v_writelane_b32 v254, s6, 34
	s_add_u32 s72, s2, 0x24600000
	s_addc_u32 s73, s3, 0
	v_writelane_b32 v254, s7, 35
	v_cmp_lt_i32_e64 s[6:7], 9, v169
	s_add_u32 s74, s2, 0x26800000
	s_addc_u32 s75, s3, 0
	v_writelane_b32 v254, s6, 36
	s_add_u32 s76, s2, 0x1ad00000
	s_addc_u32 s77, s3, 0
	v_writelane_b32 v254, s7, 37
	v_cmp_lt_i32_e64 s[6:7], 10, v169
	s_add_u32 s78, s2, 0x23500000
	s_addc_u32 s79, s3, 0
	v_writelane_b32 v254, s6, 38
	s_add_u32 s22, s2, 0x25700000
	s_addc_u32 s23, s3, 0
	v_writelane_b32 v254, s7, 39
	v_cmp_lt_i32_e64 s[6:7], 11, v169
	s_add_u32 s2, s2, 0xd880000
	s_addc_u32 s3, s3, 0
	v_writelane_b32 v254, s6, 40
	s_lshl_b64 s[10:11], s[10:11], 2
	s_mul_i32 s13, s20, 0x3c0000
	v_writelane_b32 v254, s7, 41
	v_cmp_lt_i32_e64 s[6:7], 12, v169
	v_and_b32_e32 v2, 0xffffff80, v90
	v_and_b32_e32 v1, 63, v90
	v_writelane_b32 v254, s6, 42
	v_lshlrev_b32_e32 v4, 7, v2
	v_cmp_eq_u32_e64 s[44:45], 0, v1
	v_writelane_b32 v254, s7, 43
	v_cmp_lt_i32_e64 s[6:7], 13, v169
	v_or_b32_e32 v6, 0x180, v4
	v_or_b32_e32 v8, 0x100, v4
	v_writelane_b32 v254, s6, 44
	v_or_b32_e32 v10, 0x80, v4
	v_ashrrev_i32_e32 v3, 31, v2
	v_writelane_b32 v254, s7, 45
	v_cmp_lt_i32_e64 s[6:7], 14, v169
	v_lshlrev_b32_e32 v13, 5, v94
	v_ashrrev_i32_e32 v1, 31, v0
	v_writelane_b32 v254, s6, 46
	v_ashrrev_i32_e32 v7, 31, v6
	v_ashrrev_i32_e32 v9, 31, v8
	v_writelane_b32 v254, s7, 47
	v_cmp_lt_i32_e64 s[6:7], 15, v169
	v_ashrrev_i32_e32 v11, 31, v10
	v_ashrrev_i32_e32 v5, 31, v4
	v_writelane_b32 v254, s6, 48
	v_lshl_add_u32 v171, v90, 2, 0
	v_lshlrev_b32_e32 v172, 2, v94
	v_writelane_b32 v254, s7, 49
	v_cmp_lt_i32_e64 s[6:7], 16, v169
	v_lshl_add_u64 v[96:97], v[90:91], 1, s[2:3]
	v_lshl_add_u64 v[116:117], v[0:1], 1, s[2:3]
	v_writelane_b32 v254, s6, 50
	v_add_u32_e32 v173, v12, v13
	s_mov_b32 s80, s70
	v_writelane_b32 v254, s7, 51
	v_writelane_b32 v254, s1, 52
	s_mov_b64 s[6:7], s[18:19]
	v_writelane_b32 v254, s0, 53
	s_load_dwordx2 s[0:1], s[18:19], 0xe0
	s_nop 0
	s_load_dwordx4 s[16:19], s[6:7], 0xd0
	v_writelane_b32 v254, s6, 54
	s_waitcnt lgkmcnt(0)
	s_add_u32 s10, s16, s10
	v_writelane_b32 v254, s7, 55
	s_load_dwordx2 s[6:7], s[6:7], 0x28
	s_addc_u32 s11, s17, s11
	s_add_u32 s14, s14, s8
	s_addc_u32 s15, s15, s9
	s_add_u32 s16, s18, s8
	s_addc_u32 s17, s19, s9
	s_waitcnt lgkmcnt(0)
	s_add_u32 s6, s6, s13
	s_addc_u32 s7, s7, 0
	s_add_u32 s4, s4, s8
	s_addc_u32 s5, s5, s9
	s_add_u32 s0, s0, s8
	s_addc_u32 s1, s1, s9
	v_lshl_add_u64 v[100:101], s[0:1], 0, v[92:93]
	s_lshl_b32 s0, s20, 7
	v_writelane_b32 v254, s0, 56
	v_writelane_b32 v254, s31, 57
	v_writelane_b32 v254, s22, 58
	v_readlane_b32 s0, v253, 34
	v_lshl_add_u64 v[104:105], v[2:3], 2, s[16:17]
	v_writelane_b32 v254, s23, 59
	s_add_i32 s16, s0, s12
	v_readlane_b32 s0, v253, 37
	v_writelane_b32 v254, s44, 60
	v_lshl_add_u64 v[98:99], s[6:7], 0, v[92:93]
	v_lshl_add_u64 v[102:103], s[4:5], 0, v[92:93]
	v_lshl_add_u64 v[106:107], v[4:5], 2, s[10:11]
	v_lshl_add_u64 v[108:109], v[10:11], 2, s[10:11]
	v_lshl_add_u64 v[110:111], v[8:9], 2, s[10:11]
	v_lshl_add_u64 v[112:113], v[6:7], 2, s[10:11]
	v_lshl_add_u64 v[114:115], v[0:1], 2, s[14:15]
	s_mov_b32 s18, s0
	v_writelane_b32 v254, s45, 61
	s_branch .LBB0_781
